# P11 indexer: per-token MFMA chains with other token epilogue overlapped, permlane32 swap instead of bpermute, counted vmcnt; P13: direct K prefetch loads, counted vmcnt
# speedup vs baseline: 1.0121x; 1.0121x over previous
; #define LAS __attribute__((address_space(3)))
; DI void indexer_tile(const LAS unsigned char* buf, const f16x8 (&af)[2][8], const f32x4 (&wv)[2][4], float* sc0, float* sc1, int kt, int r32, int h2) {
;     ...
;         for (int ks = 0; ks < 8; ++ks) bfr[sub][ks] = *(const LAS f16x8*)(buf + (32 * sub + r32) * KT_ROWB + (16 * ks + 8 * h2) * 2);
;     __builtin_amdgcn_sched_barrier(0);
; #pragma unroll
;     for (int sub = 0; sub < 2; ++sub) {
;         f32x16 c0, c1;
; #pragma unroll
;         for (int i = 0; i < 16; ++i) { c0[i] = 0.f; c1[i] = 0.f; }
; #pragma unroll
;         for (int ks = 0; ks < 8; ++ks) { c0 = __builtin_amdgcn_mfma_f32_32x32x16_f16(af[0][ks], bfr[sub][ks], c0, 0, 0, 0); c1 = __builtin_amdgcn_mfma_f32_32x32x16_f16(af[1][ks], bfr[sub][ks], c1, 0, 0, 0); }
;         f32x2_t a0 = {0.f, 0.f}, a1 = {0.f, 0.f};
; #pragma unroll
;         for (int q = 0; q < 4; ++q)
; #pragma unroll
;             for (int e = 0; e < 4; e += 2) {
;                 const f32x2_t r0 = {relu1(c0[4 * q + e]), relu1(c0[4 * q + e + 1])};
;                 const f32x2_t r1 = {relu1(c1[4 * q + e]), relu1(c1[4 * q + e + 1])};
;                 const f32x2_t w0 = {wv[0][q][e], wv[0][q][e + 1]}, w1 = {wv[1][q][e], wv[1][q][e + 1]};
;                 a0 = __builtin_elementwise_fma(r0, w0, a0); a1 = __builtin_elementwise_fma(r1, w1, a1); }
;         float s0 = a0.x + a0.y, s1 = a1.x + a1.y;
;         s0 += __shfl_xor(s0, 32); s1 += __shfl_xor(s1, 32);
;         if (h2 == 0) { sc0[kt * 64 + 32 * sub + r32] = s0; sc1[kt * 64 + 32 * sub + r32] = s1; }
.LBB0_1827:
	ds_read_b128 v[0:3], v207
	ds_read_b128 v[210:213], v207 offset:32
	ds_read_b128 v[214:217], v207 offset:64
	ds_read_b128 v[218:221], v207 offset:96
	ds_read_b128 v[222:225], v207 offset:128
	ds_read_b128 v[226:229], v207 offset:160
	ds_read_b128 v[230:233], v207 offset:192
	ds_read_b128 v[234:237], v207 offset:224
	ds_read_b128 v[176:179], v207 offset:8704
	ds_read_b128 v[172:175], v207 offset:8736
	ds_read_b128 v[168:171], v207 offset:8768
	ds_read_b128 v[164:167], v207 offset:8800
	ds_read_b128 v[160:163], v207 offset:8832
	ds_read_b128 v[156:159], v207 offset:8864
	ds_read_b128 v[152:155], v207 offset:8896
	ds_read_b128 v[148:151], v207 offset:8928
	s_waitcnt lgkmcnt(15)
	v_mfma_f32_32x32x16_f16 v[16:31], v[36:39], v[0:3], 0
	s_waitcnt lgkmcnt(14)
	v_mfma_f32_32x32x16_f16 v[16:31], v[40:43], v[210:213], v[16:31]
	s_waitcnt lgkmcnt(13)
	v_mfma_f32_32x32x16_f16 v[16:31], v[44:47], v[214:217], v[16:31]
	s_waitcnt lgkmcnt(12)
	v_mfma_f32_32x32x16_f16 v[16:31], v[48:51], v[218:221], v[16:31]
	s_waitcnt lgkmcnt(11)
	v_mfma_f32_32x32x16_f16 v[16:31], v[52:55], v[222:225], v[16:31]
	s_waitcnt lgkmcnt(10)
	v_mfma_f32_32x32x16_f16 v[16:31], v[56:59], v[226:229], v[16:31]
	s_waitcnt lgkmcnt(9)
	v_mfma_f32_32x32x16_f16 v[16:31], v[60:63], v[230:233], v[16:31]
	s_waitcnt lgkmcnt(8)
	v_mfma_f32_32x32x16_f16 v[16:31], v[64:67], v[234:237], v[16:31]
	v_mfma_f32_32x32x16_f16 v[0:15], v[84:87], v[0:3], 0
	v_mfma_f32_32x32x16_f16 v[0:15], v[88:91], v[210:213], v[0:15]
	v_mfma_f32_32x32x16_f16 v[0:15], v[92:95], v[214:217], v[0:15]
	s_nop 8
	v_max_i32_e32 v16, 0, v16
	v_max_i32_e32 v17, 0, v17
	v_fma_f32 v238, v16, v68, 0
	v_fma_f32 v239, v17, v69, 0
	v_max_i32_e32 v18, 0, v18
	v_max_i32_e32 v19, 0, v19
	v_fma_f32 v238, v18, v70, v238
	v_mfma_f32_32x32x16_f16 v[0:15], v[96:99], v[218:221], v[0:15]
	v_fma_f32 v239, v19, v71, v239
	v_max_i32_e32 v20, 0, v20
	v_max_i32_e32 v21, 0, v21
	v_fma_f32 v238, v20, v72, v238
	v_fma_f32 v239, v21, v73, v239
	v_max_i32_e32 v22, 0, v22
	v_max_i32_e32 v23, 0, v23
	v_mfma_f32_32x32x16_f16 v[0:15], v[100:103], v[222:225], v[0:15]
	v_fma_f32 v238, v22, v74, v238
	v_fma_f32 v239, v23, v75, v239
	v_max_i32_e32 v24, 0, v24
	v_max_i32_e32 v25, 0, v25
	v_fma_f32 v238, v24, v76, v238
	v_fma_f32 v239, v25, v77, v239
	v_mfma_f32_32x32x16_f16 v[0:15], v[104:107], v[226:229], v[0:15]
	v_max_i32_e32 v26, 0, v26
	v_max_i32_e32 v27, 0, v27
	v_fma_f32 v238, v26, v78, v238
	v_fma_f32 v239, v27, v79, v239
	v_max_i32_e32 v28, 0, v28
	v_max_i32_e32 v29, 0, v29
	v_mfma_f32_32x32x16_f16 v[0:15], v[108:111], v[230:233], v[0:15]
	v_fma_f32 v238, v28, v80, v238
	v_fma_f32 v239, v29, v81, v239
	v_max_i32_e32 v30, 0, v30
	v_max_i32_e32 v31, 0, v31
	v_fma_f32 v238, v30, v82, v238
	v_fma_f32 v239, v31, v83, v239
	v_mfma_f32_32x32x16_f16 v[0:15], v[112:115], v[234:237], v[0:15]
	v_add_f32_e32 v240, v238, v239
	v_mov_b32_e32 v241, v240
	v_lshlrev_b32_e32 v242, 2, v32
	s_nop 0
	v_permlane32_swap_b32_e32 v241, v240
	v_add_f32_e32 v241, v241, v240
	s_mov_b64 exec, s[4:5]
	global_store_dword v242, v241, s[18:19]
	s_mov_b64 exec, -1
	s_waitcnt lgkmcnt(0)
; #define LAS __attribute__((address_space(3)))
; DI void indexer_tile(const LAS unsigned char* buf, const f16x8 (&af)[2][8], const f32x4 (&wv)[2][4], float* sc0, float* sc1, int kt, int r32, int h2) {
;     ...
;     for (int sub = 0; sub < 2; ++sub) {
;         f32x16 c0, c1;
; #pragma unroll
;         for (int i = 0; i < 16; ++i) { c0[i] = 0.f; c1[i] = 0.f; }
; #pragma unroll
;         for (int ks = 0; ks < 8; ++ks) { c0 = __builtin_amdgcn_mfma_f32_32x32x16_f16(af[0][ks], bfr[sub][ks], c0, 0, 0, 0); c1 = __builtin_amdgcn_mfma_f32_32x32x16_f16(af[1][ks], bfr[sub][ks], c1, 0, 0, 0); }
;         f32x2_t a0 = {0.f, 0.f}, a1 = {0.f, 0.f};
; #pragma unroll
;         for (int q = 0; q < 4; ++q)
; #pragma unroll
;             for (int e = 0; e < 4; e += 2) {
;                 const f32x2_t r0 = {relu1(c0[4 * q + e]), relu1(c0[4 * q + e + 1])};
;                 const f32x2_t r1 = {relu1(c1[4 * q + e]), relu1(c1[4 * q + e + 1])};
;                 const f32x2_t w0 = {wv[0][q][e], wv[0][q][e + 1]}, w1 = {wv[1][q][e], wv[1][q][e + 1]};
;                 a0 = __builtin_elementwise_fma(r0, w0, a0); a1 = __builtin_elementwise_fma(r1, w1, a1); }
;         float s0 = a0.x + a0.y, s1 = a1.x + a1.y;
;         s0 += __shfl_xor(s0, 32); s1 += __shfl_xor(s1, 32);
;         if (h2 == 0) { sc0[kt * 64 + 32 * sub + r32] = s0; sc1[kt * 64 + 32 * sub + r32] = s1; }
; DI void indexer_phase(const unsigned short* QI, const unsigned short* KI16, const float* WI, float* SC, LAS unsigned char* lds, int tid, int bid, int G) {
;     ...
;                 if (kt + 1 < nt) { *(LAS u32x4*)(buf1 + key0 * KT_ROWB + ch * 16) = b0; *(LAS u32x4*)(buf1 + (key0 + 32) * KT_ROWB + ch * 16) = b1; }
	v_mfma_f32_32x32x16_f16 v[16:31], v[36:39], v[176:179], 0
	v_mfma_f32_32x32x16_f16 v[16:31], v[40:43], v[172:175], v[16:31]
	v_mfma_f32_32x32x16_f16 v[16:31], v[44:47], v[168:171], v[16:31]
	s_nop 8
	v_max_i32_e32 v0, 0, v0
	v_max_i32_e32 v1, 0, v1
	v_fma_f32 v243, v0, v116, 0
	v_fma_f32 v244, v1, v117, 0
	v_max_i32_e32 v2, 0, v2
	v_max_i32_e32 v3, 0, v3
	v_fma_f32 v243, v2, v118, v243
	v_mfma_f32_32x32x16_f16 v[16:31], v[48:51], v[164:167], v[16:31]
	v_fma_f32 v244, v3, v119, v244
	v_max_i32_e32 v4, 0, v4
	v_max_i32_e32 v5, 0, v5
	v_fma_f32 v243, v4, v120, v243
	v_fma_f32 v244, v5, v121, v244
	v_max_i32_e32 v6, 0, v6
	v_max_i32_e32 v7, 0, v7
	v_mfma_f32_32x32x16_f16 v[16:31], v[52:55], v[160:163], v[16:31]
	v_fma_f32 v243, v6, v122, v243
	v_fma_f32 v244, v7, v123, v244
	v_max_i32_e32 v8, 0, v8
	v_max_i32_e32 v9, 0, v9
	v_fma_f32 v243, v8, v124, v243
	v_fma_f32 v244, v9, v125, v244
	v_mfma_f32_32x32x16_f16 v[16:31], v[56:59], v[156:159], v[16:31]
	v_max_i32_e32 v10, 0, v10
	v_max_i32_e32 v11, 0, v11
	v_fma_f32 v243, v10, v126, v243
	v_fma_f32 v244, v11, v127, v244
	v_max_i32_e32 v12, 0, v12
	v_max_i32_e32 v13, 0, v13
	v_mfma_f32_32x32x16_f16 v[16:31], v[60:63], v[152:155], v[16:31]
	v_fma_f32 v243, v12, v128, v243
	v_fma_f32 v244, v13, v129, v244
	v_max_i32_e32 v14, 0, v14
	v_max_i32_e32 v15, 0, v15
	v_fma_f32 v243, v14, v130, v243
	v_fma_f32 v244, v15, v131, v244
	v_mfma_f32_32x32x16_f16 v[16:31], v[64:67], v[148:151], v[16:31]
	v_add_f32_e32 v245, v243, v244
	v_mov_b32_e32 v246, v245
	v_lshlrev_b32_e32 v247, 2, v32
	s_nop 0
	v_permlane32_swap_b32_e32 v246, v245
	v_add_f32_e32 v246, v246, v245
	s_mov_b64 exec, s[4:5]
	global_store_dword v247, v246, s[20:21]
	s_mov_b64 exec, -1
	v_mfma_f32_32x32x16_f16 v[0:15], v[84:87], v[176:179], 0
	v_mfma_f32_32x32x16_f16 v[0:15], v[88:91], v[172:175], v[0:15]
	v_mfma_f32_32x32x16_f16 v[0:15], v[92:95], v[168:171], v[0:15]
	s_nop 8
	v_max_i32_e32 v16, 0, v16
	v_max_i32_e32 v17, 0, v17
	v_fma_f32 v238, v16, v68, 0
	v_fma_f32 v239, v17, v69, 0
	v_max_i32_e32 v18, 0, v18
	v_max_i32_e32 v19, 0, v19
	v_fma_f32 v238, v18, v70, v238
	v_mfma_f32_32x32x16_f16 v[0:15], v[96:99], v[164:167], v[0:15]
	v_fma_f32 v239, v19, v71, v239
	v_max_i32_e32 v20, 0, v20
	v_max_i32_e32 v21, 0, v21
	v_fma_f32 v238, v20, v72, v238
	v_fma_f32 v239, v21, v73, v239
	v_max_i32_e32 v22, 0, v22
	v_max_i32_e32 v23, 0, v23
	v_mfma_f32_32x32x16_f16 v[0:15], v[100:103], v[160:163], v[0:15]
	v_fma_f32 v238, v22, v74, v238
	v_fma_f32 v239, v23, v75, v239
	v_max_i32_e32 v24, 0, v24
	v_max_i32_e32 v25, 0, v25
	v_fma_f32 v238, v24, v76, v238
	v_fma_f32 v239, v25, v77, v239
	v_mfma_f32_32x32x16_f16 v[0:15], v[104:107], v[156:159], v[0:15]
	v_max_i32_e32 v26, 0, v26
	v_max_i32_e32 v27, 0, v27
	v_fma_f32 v238, v26, v78, v238
	v_fma_f32 v239, v27, v79, v239
	v_max_i32_e32 v28, 0, v28
	v_max_i32_e32 v29, 0, v29
	v_mfma_f32_32x32x16_f16 v[0:15], v[108:111], v[152:155], v[0:15]
	v_fma_f32 v238, v28, v80, v238
	v_fma_f32 v239, v29, v81, v239
	v_max_i32_e32 v30, 0, v30
	v_max_i32_e32 v31, 0, v31
	v_fma_f32 v238, v30, v82, v238
	v_fma_f32 v239, v31, v83, v239
	v_mfma_f32_32x32x16_f16 v[0:15], v[112:115], v[148:151], v[0:15]
	v_add_f32_e32 v240, v238, v239
	v_mov_b32_e32 v241, v240
	v_lshlrev_b32_e32 v242, 2, v32
	s_nop 0
	v_permlane32_swap_b32_e32 v241, v240
	v_add_f32_e32 v241, v241, v240
	s_mov_b64 exec, s[4:5]
	global_store_dword v242, v241, s[18:19] offset:128
	s_mov_b64 exec, -1
	s_nop 11
	v_max_i32_e32 v0, 0, v0
	v_max_i32_e32 v1, 0, v1
	v_fma_f32 v243, v0, v116, 0
	v_fma_f32 v244, v1, v117, 0
	v_max_i32_e32 v2, 0, v2
	v_max_i32_e32 v3, 0, v3
	v_fma_f32 v243, v2, v118, v243
	v_fma_f32 v244, v3, v119, v244
	v_max_i32_e32 v4, 0, v4
	v_max_i32_e32 v5, 0, v5
	v_fma_f32 v243, v4, v120, v243
	v_fma_f32 v244, v5, v121, v244
	v_max_i32_e32 v6, 0, v6
	v_max_i32_e32 v7, 0, v7
	v_fma_f32 v243, v6, v122, v243
	v_fma_f32 v244, v7, v123, v244
	v_max_i32_e32 v8, 0, v8
	v_max_i32_e32 v9, 0, v9
	v_fma_f32 v243, v8, v124, v243
	v_fma_f32 v244, v9, v125, v244
	v_max_i32_e32 v10, 0, v10
	v_max_i32_e32 v11, 0, v11
	v_fma_f32 v243, v10, v126, v243
	v_fma_f32 v244, v11, v127, v244
	v_max_i32_e32 v12, 0, v12
	v_max_i32_e32 v13, 0, v13
	v_fma_f32 v243, v12, v128, v243
	v_fma_f32 v244, v13, v129, v244
	v_max_i32_e32 v14, 0, v14
	v_max_i32_e32 v15, 0, v15
	v_fma_f32 v243, v14, v130, v243
	v_fma_f32 v244, v15, v131, v244
	v_add_f32_e32 v245, v243, v244
	v_mov_b32_e32 v246, v245
	v_lshlrev_b32_e32 v247, 2, v32
	s_nop 0
	v_permlane32_swap_b32_e32 v246, v245
	v_add_f32_e32 v246, v246, v245
	s_mov_b64 exec, s[4:5]
	global_store_dword v247, v246, s[20:21] offset:128
	s_mov_b64 exec, -1
	s_add_i32 s27, s11, -3
	s_cmp_lt_i32 s27, s41
	s_cselect_b64 s[24:25], -1, 0
	s_cmp_ge_i32 s27, s41
	s_cbranch_scc1 .LBB0_1833
	s_waitcnt vmcnt(8)
	ds_write_b128 v209, v[140:143] offset:17408
	ds_write_b128 v209, v[144:147] offset:26112

; #define LAS __attribute__((address_space(3)))
; DI void indexer_tile(const LAS unsigned char* buf, const f16x8 (&af)[2][8], const f32x4 (&wv)[2][4], float* sc0, float* sc1, int kt, int r32, int h2) {
;     ...
;         for (int ks = 0; ks < 8; ++ks) bfr[sub][ks] = *(const LAS f16x8*)(buf + (32 * sub + r32) * KT_ROWB + (16 * ks + 8 * h2) * 2);
;     __builtin_amdgcn_sched_barrier(0);
; #pragma unroll
;     for (int sub = 0; sub < 2; ++sub) {
;         f32x16 c0, c1;
; #pragma unroll
;         for (int i = 0; i < 16; ++i) { c0[i] = 0.f; c1[i] = 0.f; }
; #pragma unroll
;         for (int ks = 0; ks < 8; ++ks) { c0 = __builtin_amdgcn_mfma_f32_32x32x16_f16(af[0][ks], bfr[sub][ks], c0, 0, 0, 0); c1 = __builtin_amdgcn_mfma_f32_32x32x16_f16(af[1][ks], bfr[sub][ks], c1, 0, 0, 0); }
;         f32x2_t a0 = {0.f, 0.f}, a1 = {0.f, 0.f};
; #pragma unroll
;         for (int q = 0; q < 4; ++q)
; #pragma unroll
;             for (int e = 0; e < 4; e += 2) {
;                 const f32x2_t r0 = {relu1(c0[4 * q + e]), relu1(c0[4 * q + e + 1])};
;                 const f32x2_t r1 = {relu1(c1[4 * q + e]), relu1(c1[4 * q + e + 1])};
;                 const f32x2_t w0 = {wv[0][q][e], wv[0][q][e + 1]}, w1 = {wv[1][q][e], wv[1][q][e + 1]};
;                 a0 = __builtin_elementwise_fma(r0, w0, a0); a1 = __builtin_elementwise_fma(r1, w1, a1); }
;         float s0 = a0.x + a0.y, s1 = a1.x + a1.y;
;         s0 += __shfl_xor(s0, 32); s1 += __shfl_xor(s1, 32);
;         if (h2 == 0) { sc0[kt * 64 + 32 * sub + r32] = s0; sc1[kt * 64 + 32 * sub + r32] = s1; }
.LBB0_1836:
	ds_read_b128 v[0:3], v207 offset:17408
	ds_read_b128 v[210:213], v207 offset:17440
	ds_read_b128 v[214:217], v207 offset:17472
	ds_read_b128 v[218:221], v207 offset:17504
	ds_read_b128 v[222:225], v207 offset:17536
	ds_read_b128 v[226:229], v207 offset:17568
	ds_read_b128 v[230:233], v207 offset:17600
	ds_read_b128 v[234:237], v207 offset:17632
	ds_read_b128 v[176:179], v207 offset:26112
	ds_read_b128 v[172:175], v207 offset:26144
	ds_read_b128 v[168:171], v207 offset:26176
	ds_read_b128 v[164:167], v207 offset:26208
	ds_read_b128 v[160:163], v207 offset:26240
	ds_read_b128 v[156:159], v207 offset:26272
	ds_read_b128 v[152:155], v207 offset:26304
	ds_read_b128 v[148:151], v207 offset:26336
	s_waitcnt lgkmcnt(15)
	v_mfma_f32_32x32x16_f16 v[16:31], v[36:39], v[0:3], 0
	s_waitcnt lgkmcnt(14)
	v_mfma_f32_32x32x16_f16 v[16:31], v[40:43], v[210:213], v[16:31]
	s_waitcnt lgkmcnt(13)
	v_mfma_f32_32x32x16_f16 v[16:31], v[44:47], v[214:217], v[16:31]
	s_waitcnt lgkmcnt(12)
	v_mfma_f32_32x32x16_f16 v[16:31], v[48:51], v[218:221], v[16:31]
	s_waitcnt lgkmcnt(11)
	v_mfma_f32_32x32x16_f16 v[16:31], v[52:55], v[222:225], v[16:31]
	s_waitcnt lgkmcnt(10)
	v_mfma_f32_32x32x16_f16 v[16:31], v[56:59], v[226:229], v[16:31]
	s_waitcnt lgkmcnt(9)
	v_mfma_f32_32x32x16_f16 v[16:31], v[60:63], v[230:233], v[16:31]
	s_waitcnt lgkmcnt(8)
	v_mfma_f32_32x32x16_f16 v[16:31], v[64:67], v[234:237], v[16:31]
	v_mfma_f32_32x32x16_f16 v[0:15], v[84:87], v[0:3], 0
	v_mfma_f32_32x32x16_f16 v[0:15], v[88:91], v[210:213], v[0:15]
	v_mfma_f32_32x32x16_f16 v[0:15], v[92:95], v[214:217], v[0:15]
	s_nop 8
	v_max_i32_e32 v16, 0, v16
	v_max_i32_e32 v17, 0, v17
	v_fma_f32 v238, v16, v68, 0
	v_fma_f32 v239, v17, v69, 0
	v_max_i32_e32 v18, 0, v18
	v_max_i32_e32 v19, 0, v19
	v_fma_f32 v238, v18, v70, v238
	v_mfma_f32_32x32x16_f16 v[0:15], v[96:99], v[218:221], v[0:15]
	v_fma_f32 v239, v19, v71, v239
	v_max_i32_e32 v20, 0, v20
	v_max_i32_e32 v21, 0, v21
	v_fma_f32 v238, v20, v72, v238
	v_fma_f32 v239, v21, v73, v239
	v_max_i32_e32 v22, 0, v22
	v_max_i32_e32 v23, 0, v23
	v_mfma_f32_32x32x16_f16 v[0:15], v[100:103], v[222:225], v[0:15]
	v_fma_f32 v238, v22, v74, v238
	v_fma_f32 v239, v23, v75, v239
	v_max_i32_e32 v24, 0, v24
	v_max_i32_e32 v25, 0, v25
	v_fma_f32 v238, v24, v76, v238
	v_fma_f32 v239, v25, v77, v239
	v_mfma_f32_32x32x16_f16 v[0:15], v[104:107], v[226:229], v[0:15]
	v_max_i32_e32 v26, 0, v26
	v_max_i32_e32 v27, 0, v27
	v_fma_f32 v238, v26, v78, v238
	v_fma_f32 v239, v27, v79, v239
	v_max_i32_e32 v28, 0, v28
	v_max_i32_e32 v29, 0, v29
	v_mfma_f32_32x32x16_f16 v[0:15], v[108:111], v[230:233], v[0:15]
	v_fma_f32 v238, v28, v80, v238
	v_fma_f32 v239, v29, v81, v239
	v_max_i32_e32 v30, 0, v30
	v_max_i32_e32 v31, 0, v31
	v_fma_f32 v238, v30, v82, v238
	v_fma_f32 v239, v31, v83, v239
	v_mfma_f32_32x32x16_f16 v[0:15], v[112:115], v[234:237], v[0:15]
	v_add_f32_e32 v240, v238, v239
	v_mov_b32_e32 v241, v240
	v_lshlrev_b32_e32 v242, 2, v32
	s_nop 0
	v_permlane32_swap_b32_e32 v241, v240
	v_add_f32_e32 v241, v241, v240
	s_mov_b64 exec, s[4:5]
	global_store_dword v242, v241, s[18:19] offset:256
	s_mov_b64 exec, -1
	s_waitcnt lgkmcnt(0)
; #define LAS __attribute__((address_space(3)))
; DI void indexer_tile(const LAS unsigned char* buf, const f16x8 (&af)[2][8], const f32x4 (&wv)[2][4], float* sc0, float* sc1, int kt, int r32, int h2) {
;     ...
;     for (int sub = 0; sub < 2; ++sub) {
;         f32x16 c0, c1;
; #pragma unroll
;         for (int i = 0; i < 16; ++i) { c0[i] = 0.f; c1[i] = 0.f; }
; #pragma unroll
;         for (int ks = 0; ks < 8; ++ks) { c0 = __builtin_amdgcn_mfma_f32_32x32x16_f16(af[0][ks], bfr[sub][ks], c0, 0, 0, 0); c1 = __builtin_amdgcn_mfma_f32_32x32x16_f16(af[1][ks], bfr[sub][ks], c1, 0, 0, 0); }
;         f32x2_t a0 = {0.f, 0.f}, a1 = {0.f, 0.f};
; #pragma unroll
;         for (int q = 0; q < 4; ++q)
; #pragma unroll
;             for (int e = 0; e < 4; e += 2) {
;                 const f32x2_t r0 = {relu1(c0[4 * q + e]), relu1(c0[4 * q + e + 1])};
;                 const f32x2_t r1 = {relu1(c1[4 * q + e]), relu1(c1[4 * q + e + 1])};
;                 const f32x2_t w0 = {wv[0][q][e], wv[0][q][e + 1]}, w1 = {wv[1][q][e], wv[1][q][e + 1]};
;                 a0 = __builtin_elementwise_fma(r0, w0, a0); a1 = __builtin_elementwise_fma(r1, w1, a1); }
;         float s0 = a0.x + a0.y, s1 = a1.x + a1.y;
;         s0 += __shfl_xor(s0, 32); s1 += __shfl_xor(s1, 32);
;         if (h2 == 0) { sc0[kt * 64 + 32 * sub + r32] = s0; sc1[kt * 64 + 32 * sub + r32] = s1; }
; DI void indexer_phase(const unsigned short* QI, const unsigned short* KI16, const float* WI, float* SC, LAS unsigned char* lds, int tid, int bid, int G) {
;     ...
;                 if (kt + 2 < nt) { *(LAS u32x4*)(buf0 + key0 * KT_ROWB + ch * 16) = a0; *(LAS u32x4*)(buf0 + (key0 + 32) * KT_ROWB + ch * 16) = a1; }
	v_mfma_f32_32x32x16_f16 v[16:31], v[36:39], v[176:179], 0
	v_mfma_f32_32x32x16_f16 v[16:31], v[40:43], v[172:175], v[16:31]
	v_mfma_f32_32x32x16_f16 v[16:31], v[44:47], v[168:171], v[16:31]
	s_nop 8
	v_max_i32_e32 v0, 0, v0
	v_max_i32_e32 v1, 0, v1
	v_fma_f32 v243, v0, v116, 0
	v_fma_f32 v244, v1, v117, 0
	v_max_i32_e32 v2, 0, v2
	v_max_i32_e32 v3, 0, v3
	v_fma_f32 v243, v2, v118, v243
	v_mfma_f32_32x32x16_f16 v[16:31], v[48:51], v[164:167], v[16:31]
	v_fma_f32 v244, v3, v119, v244
	v_max_i32_e32 v4, 0, v4
	v_max_i32_e32 v5, 0, v5
	v_fma_f32 v243, v4, v120, v243
	v_fma_f32 v244, v5, v121, v244
	v_max_i32_e32 v6, 0, v6
	v_max_i32_e32 v7, 0, v7
	v_mfma_f32_32x32x16_f16 v[16:31], v[52:55], v[160:163], v[16:31]
	v_fma_f32 v243, v6, v122, v243
	v_fma_f32 v244, v7, v123, v244
	v_max_i32_e32 v8, 0, v8
	v_max_i32_e32 v9, 0, v9
	v_fma_f32 v243, v8, v124, v243
	v_fma_f32 v244, v9, v125, v244
	v_mfma_f32_32x32x16_f16 v[16:31], v[56:59], v[156:159], v[16:31]
	v_max_i32_e32 v10, 0, v10
	v_max_i32_e32 v11, 0, v11
	v_fma_f32 v243, v10, v126, v243
	v_fma_f32 v244, v11, v127, v244
	v_max_i32_e32 v12, 0, v12
	v_max_i32_e32 v13, 0, v13
	v_mfma_f32_32x32x16_f16 v[16:31], v[60:63], v[152:155], v[16:31]
	v_fma_f32 v243, v12, v128, v243
	v_fma_f32 v244, v13, v129, v244
	v_max_i32_e32 v14, 0, v14
	v_max_i32_e32 v15, 0, v15
	v_fma_f32 v243, v14, v130, v243
	v_fma_f32 v244, v15, v131, v244
	v_mfma_f32_32x32x16_f16 v[16:31], v[64:67], v[148:151], v[16:31]
	v_add_f32_e32 v245, v243, v244
	v_mov_b32_e32 v246, v245
	v_lshlrev_b32_e32 v247, 2, v32
	s_nop 0
	v_permlane32_swap_b32_e32 v246, v245
	v_add_f32_e32 v246, v246, v245
	s_mov_b64 exec, s[4:5]
	global_store_dword v247, v246, s[20:21] offset:256
	s_mov_b64 exec, -1
	v_mfma_f32_32x32x16_f16 v[0:15], v[84:87], v[176:179], 0
	v_mfma_f32_32x32x16_f16 v[0:15], v[88:91], v[172:175], v[0:15]
	v_mfma_f32_32x32x16_f16 v[0:15], v[92:95], v[168:171], v[0:15]
	s_nop 8
	v_max_i32_e32 v16, 0, v16
	v_max_i32_e32 v17, 0, v17
	v_fma_f32 v238, v16, v68, 0
	v_fma_f32 v239, v17, v69, 0
	v_max_i32_e32 v18, 0, v18
	v_max_i32_e32 v19, 0, v19
	v_fma_f32 v238, v18, v70, v238
	v_mfma_f32_32x32x16_f16 v[0:15], v[96:99], v[164:167], v[0:15]
	v_fma_f32 v239, v19, v71, v239
	v_max_i32_e32 v20, 0, v20
	v_max_i32_e32 v21, 0, v21
	v_fma_f32 v238, v20, v72, v238
	v_fma_f32 v239, v21, v73, v239
	v_max_i32_e32 v22, 0, v22
	v_max_i32_e32 v23, 0, v23
	v_mfma_f32_32x32x16_f16 v[0:15], v[100:103], v[160:163], v[0:15]
	v_fma_f32 v238, v22, v74, v238
	v_fma_f32 v239, v23, v75, v239
	v_max_i32_e32 v24, 0, v24
	v_max_i32_e32 v25, 0, v25
	v_fma_f32 v238, v24, v76, v238
	v_fma_f32 v239, v25, v77, v239
	v_mfma_f32_32x32x16_f16 v[0:15], v[104:107], v[156:159], v[0:15]
	v_max_i32_e32 v26, 0, v26
	v_max_i32_e32 v27, 0, v27
	v_fma_f32 v238, v26, v78, v238
	v_fma_f32 v239, v27, v79, v239
	v_max_i32_e32 v28, 0, v28
	v_max_i32_e32 v29, 0, v29
	v_mfma_f32_32x32x16_f16 v[0:15], v[108:111], v[152:155], v[0:15]
	v_fma_f32 v238, v28, v80, v238
	v_fma_f32 v239, v29, v81, v239
	v_max_i32_e32 v30, 0, v30
	v_max_i32_e32 v31, 0, v31
	v_fma_f32 v238, v30, v82, v238
	v_fma_f32 v239, v31, v83, v239
	v_mfma_f32_32x32x16_f16 v[0:15], v[112:115], v[148:151], v[0:15]
	v_add_f32_e32 v240, v238, v239
	v_mov_b32_e32 v241, v240
	v_lshlrev_b32_e32 v242, 2, v32
	s_nop 0
	v_permlane32_swap_b32_e32 v241, v240
	v_add_f32_e32 v241, v241, v240
	s_mov_b64 exec, s[4:5]
	global_store_dword v242, v241, s[18:19] offset:384
	s_mov_b64 exec, -1
	s_nop 11
	v_max_i32_e32 v0, 0, v0
	v_max_i32_e32 v1, 0, v1
	v_fma_f32 v243, v0, v116, 0
	v_fma_f32 v244, v1, v117, 0
	v_max_i32_e32 v2, 0, v2
	v_max_i32_e32 v3, 0, v3
	v_fma_f32 v243, v2, v118, v243
	v_fma_f32 v244, v3, v119, v244
	v_max_i32_e32 v4, 0, v4
	v_max_i32_e32 v5, 0, v5
	v_fma_f32 v243, v4, v120, v243
	v_fma_f32 v244, v5, v121, v244
	v_max_i32_e32 v6, 0, v6
	v_max_i32_e32 v7, 0, v7
	v_fma_f32 v243, v6, v122, v243
	v_fma_f32 v244, v7, v123, v244
	v_max_i32_e32 v8, 0, v8
	v_max_i32_e32 v9, 0, v9
	v_fma_f32 v243, v8, v124, v243
	v_fma_f32 v244, v9, v125, v244
	v_max_i32_e32 v10, 0, v10
	v_max_i32_e32 v11, 0, v11
	v_fma_f32 v243, v10, v126, v243
	v_fma_f32 v244, v11, v127, v244
	v_max_i32_e32 v12, 0, v12
	v_max_i32_e32 v13, 0, v13
	v_fma_f32 v243, v12, v128, v243
	v_fma_f32 v244, v13, v129, v244
	v_max_i32_e32 v14, 0, v14
	v_max_i32_e32 v15, 0, v15
	v_fma_f32 v243, v14, v130, v243
	v_fma_f32 v244, v15, v131, v244
	v_add_f32_e32 v245, v243, v244
	v_mov_b32_e32 v246, v245
	v_lshlrev_b32_e32 v247, 2, v32
	s_nop 0
	v_permlane32_swap_b32_e32 v246, v245
	v_add_f32_e32 v246, v246, v245
	s_mov_b64 exec, s[4:5]
	global_store_dword v247, v246, s[20:21] offset:384
	s_mov_b64 exec, -1
	s_andn2_b64 vcc, exec, s[22:23]
	s_cbranch_vccnz .LBB0_1824
	s_waitcnt vmcnt(8)
	ds_write_b128 v209, v[132:135]
	ds_write_b128 v209, v[136:139] offset:8704
	s_branch .LBB0_1824

; #define LAS __attribute__((address_space(3)))
; DI size_t sc_row_off(int b, int s) { const int qb = s >> 7; return ((size_t)(b * 2080 + ((qb * (qb + 1)) >> 1))) * 16384 + (size_t)(s & 127) * ((qb + 1) * 128); }
; DI void indexer_phase(const unsigned short* QI, const unsigned short* KI16, const float* WI, float* SC, LAS unsigned char* lds, int tid, int bid, int G) {
;     ...
;         for (int it = 0; it < 4; ++it) {
;             const int b = it >> 1, gi = (it & 1) ? (511 - v) : v; const int tb = 16 * gi;
;             const int nt = ((tb + 15) >> 6) + 1;
;             f16x8 af[2][8]; f32x4 wv[2][4];
; #pragma unroll
;             for (int tq = 0; tq < 2; ++tq) { const size_t tg = (size_t)b * SEQ + tb + 2 * w + tq;
; #pragma unroll
;                 for (int ks = 0; ks < 8; ++ks) af[tq][ks] = *(const f16x8*)(QI + tg * 4096 + r32 * 128 + 16 * ks + 8 * h2);
; #pragma unroll
;                 for (int q = 0; q < 4; ++q) wv[tq][q] = *(const f32x4*)(WI + tg * 32 + 8 * q + 4 * h2); }
;             float* sc0 = SC + sc_row_off(b, tb + 2 * w); float* sc1 = SC + sc_row_off(b, tb + 2 * w + 1);
;             const unsigned short* src = KI16 + (size_t)b * SEQ * 128 + (size_t)key0 * 128 + ch * 8;
;             u32x4 a0, a1, b0 = {0u, 0u, 0u, 0u}, b1 = {0u, 0u, 0u, 0u};
;             a0 = *(const u32x4*)src; a1 = *(const u32x4*)(src + 32 * 128);
;             if (nt > 1) { b0 = *(const u32x4*)(src + 64 * 128); b1 = *(const u32x4*)(src + 96 * 128); }
;             __syncthreads();
;             *(LAS u32x4*)(buf0 + key0 * KT_ROWB + ch * 16) = a0; *(LAS u32x4*)(buf0 + (key0 + 32) * KT_ROWB + ch * 16) = a1;
;             __syncthreads();
.LBB0_1843:
	s_sub_i32 s11, 0x1ff, s40
	s_lshl_b32 s45, s11, 4
	s_add_u32 s18, s45, s36
	s_addc_u32 s19, 0, s37
	s_lshl_b64 s[20:21], s[18:19], 13
	v_lshl_add_u64 v[0:1], v[180:181], 0, s[20:21]
	s_lshl_b64 s[20:21], s[18:19], 7
	s_or_b32 s18, s18, 1
	global_load_dwordx4 v[34:37], v[0:1], off
	global_load_dwordx4 v[38:41], v[0:1], off offset:32
	global_load_dwordx4 v[42:45], v[0:1], off offset:64
	global_load_dwordx4 v[46:49], v[0:1], off offset:96
	global_load_dwordx4 v[50:53], v[0:1], off offset:128
	global_load_dwordx4 v[54:57], v[0:1], off offset:160
	global_load_dwordx4 v[58:61], v[0:1], off offset:192
	global_load_dwordx4 v[62:65], v[0:1], off offset:224
	v_lshl_add_u64 v[0:1], v[182:183], 0, s[20:21]
	s_lshl_b64 s[20:21], s[18:19], 13
	global_load_dwordx4 v[66:69], v[0:1], off
	global_load_dwordx4 v[70:73], v[0:1], off offset:32
	global_load_dwordx4 v[74:77], v[0:1], off offset:64
	global_load_dwordx4 v[78:81], v[0:1], off offset:96
	v_lshl_add_u64 v[0:1], v[180:181], 0, s[20:21]
	global_load_dwordx4 v[82:85], v[0:1], off
	global_load_dwordx4 v[86:89], v[0:1], off offset:32
	global_load_dwordx4 v[90:93], v[0:1], off offset:64
	global_load_dwordx4 v[94:97], v[0:1], off offset:96
	global_load_dwordx4 v[98:101], v[0:1], off offset:128
	global_load_dwordx4 v[102:105], v[0:1], off offset:160
	global_load_dwordx4 v[106:109], v[0:1], off offset:192
	global_load_dwordx4 v[110:113], v[0:1], off offset:224
	s_lshl_b64 s[18:19], s[18:19], 7
	v_lshl_add_u64 v[0:1], v[182:183], 0, s[18:19]
	global_load_dwordx4 v[130:133], v[184:185], off
	global_load_dwordx4 v[138:141], v[186:187], off
	global_load_dwordx4 v[114:117], v[0:1], off
	global_load_dwordx4 v[118:121], v[0:1], off offset:32
	global_load_dwordx4 v[134:137], v[190:191], off
	global_load_dwordx4 v[142:145], v[188:189], off
	global_load_dwordx4 v[122:125], v[0:1], off offset:64
	global_load_dwordx4 v[126:129], v[0:1], off offset:96
	s_lshr_b32 s42, s11, 2
	s_add_i32 s11, s45, s36
	s_ashr_i32 s18, s11, 7
	s_add_i32 s19, s18, 1
	s_mul_i32 s18, s19, s18
	s_ashr_i32 s18, s18, 1
	s_lshl_b32 s26, s19, 7
	s_ashr_i32 s19, s18, 31
	s_and_b32 s11, s11, 0x7e
	s_lshl_b64 s[22:23], s[18:19], 16
	s_mul_hi_i32 s21, s26, s11
	s_mul_i32 s20, s26, s11
	s_add_u32 s27, s17, s22
	s_addc_u32 s28, s33, s23
	s_lshl_b64 s[20:21], s[20:21], 2
	s_add_u32 s24, s27, s20
	s_addc_u32 s25, s28, s21
	s_or_b32 s11, s11, 1
	s_mul_hi_i32 s23, s26, s11
	s_mul_i32 s22, s26, s11
	s_lshl_b64 s[22:23], s[22:23], 2
	s_add_u32 s26, s27, s22
	s_addc_u32 s27, s28, s23
	s_mov_b32 s11, 3
	v_mov_b32_e32 v32, v206
	v_mov_b64_e32 v[178:179], v[200:201]
	s_barrier
	s_waitcnt vmcnt(7)
	ds_write_b128 v209, v[130:133]
	s_waitcnt vmcnt(0)
	ds_write_b128 v209, v[138:141] offset:8704
	s_waitcnt lgkmcnt(0)
	s_barrier
	s_branch .LBB0_1845

; #define LAS __attribute__((address_space(3)))
; DI void indexer_tile(const LAS unsigned char* buf, const f16x8 (&af)[2][8], const f32x4 (&wv)[2][4], float* sc0, float* sc1, int kt, int r32, int h2) {
;     ...
;         for (int ks = 0; ks < 8; ++ks) bfr[sub][ks] = *(const LAS f16x8*)(buf + (32 * sub + r32) * KT_ROWB + (16 * ks + 8 * h2) * 2);
;     __builtin_amdgcn_sched_barrier(0);
; #pragma unroll
;     for (int sub = 0; sub < 2; ++sub) {
;         f32x16 c0, c1;
; #pragma unroll
;         for (int i = 0; i < 16; ++i) { c0[i] = 0.f; c1[i] = 0.f; }
; #pragma unroll
;         for (int ks = 0; ks < 8; ++ks) { c0 = __builtin_amdgcn_mfma_f32_32x32x16_f16(af[0][ks], bfr[sub][ks], c0, 0, 0, 0); c1 = __builtin_amdgcn_mfma_f32_32x32x16_f16(af[1][ks], bfr[sub][ks], c1, 0, 0, 0); }
;         f32x2_t a0 = {0.f, 0.f}, a1 = {0.f, 0.f};
; #pragma unroll
;         for (int q = 0; q < 4; ++q)
; #pragma unroll
;             for (int e = 0; e < 4; e += 2) {
;                 const f32x2_t r0 = {relu1(c0[4 * q + e]), relu1(c0[4 * q + e + 1])};
;                 const f32x2_t r1 = {relu1(c1[4 * q + e]), relu1(c1[4 * q + e + 1])};
;                 const f32x2_t w0 = {wv[0][q][e], wv[0][q][e + 1]}, w1 = {wv[1][q][e], wv[1][q][e + 1]};
;                 a0 = __builtin_elementwise_fma(r0, w0, a0); a1 = __builtin_elementwise_fma(r1, w1, a1); }
;         float s0 = a0.x + a0.y, s1 = a1.x + a1.y;
;         s0 += __shfl_xor(s0, 32); s1 += __shfl_xor(s1, 32);
;         if (h2 == 0) { sc0[kt * 64 + 32 * sub + r32] = s0; sc1[kt * 64 + 32 * sub + r32] = s1; }
.LBB0_1847:
	ds_read_b128 v[0:3], v207
	ds_read_b128 v[210:213], v207 offset:32
	ds_read_b128 v[214:217], v207 offset:64
	ds_read_b128 v[218:221], v207 offset:96
	ds_read_b128 v[222:225], v207 offset:128
	ds_read_b128 v[226:229], v207 offset:160
	ds_read_b128 v[230:233], v207 offset:192
	ds_read_b128 v[234:237], v207 offset:224
	ds_read_b128 v[174:177], v207 offset:8704
	ds_read_b128 v[170:173], v207 offset:8736
	ds_read_b128 v[166:169], v207 offset:8768
	ds_read_b128 v[162:165], v207 offset:8800
	ds_read_b128 v[158:161], v207 offset:8832
	ds_read_b128 v[154:157], v207 offset:8864
	ds_read_b128 v[150:153], v207 offset:8896
	ds_read_b128 v[146:149], v207 offset:8928
	s_waitcnt lgkmcnt(15)
	v_mfma_f32_32x32x16_f16 v[16:31], v[34:37], v[0:3], 0
	s_waitcnt lgkmcnt(14)
	v_mfma_f32_32x32x16_f16 v[16:31], v[38:41], v[210:213], v[16:31]
	s_waitcnt lgkmcnt(13)
	v_mfma_f32_32x32x16_f16 v[16:31], v[42:45], v[214:217], v[16:31]
	s_waitcnt lgkmcnt(12)
	v_mfma_f32_32x32x16_f16 v[16:31], v[46:49], v[218:221], v[16:31]
	s_waitcnt lgkmcnt(11)
	v_mfma_f32_32x32x16_f16 v[16:31], v[50:53], v[222:225], v[16:31]
	s_waitcnt lgkmcnt(10)
	v_mfma_f32_32x32x16_f16 v[16:31], v[54:57], v[226:229], v[16:31]
	s_waitcnt lgkmcnt(9)
	v_mfma_f32_32x32x16_f16 v[16:31], v[58:61], v[230:233], v[16:31]
	s_waitcnt lgkmcnt(8)
	v_mfma_f32_32x32x16_f16 v[16:31], v[62:65], v[234:237], v[16:31]
	v_mfma_f32_32x32x16_f16 v[0:15], v[82:85], v[0:3], 0
	v_mfma_f32_32x32x16_f16 v[0:15], v[86:89], v[210:213], v[0:15]
	v_mfma_f32_32x32x16_f16 v[0:15], v[90:93], v[214:217], v[0:15]
	s_nop 8
	v_max_i32_e32 v16, 0, v16
	v_max_i32_e32 v17, 0, v17
	v_fma_f32 v238, v16, v66, 0
	v_fma_f32 v239, v17, v67, 0
	v_max_i32_e32 v18, 0, v18
	v_max_i32_e32 v19, 0, v19
	v_fma_f32 v238, v18, v68, v238
	v_mfma_f32_32x32x16_f16 v[0:15], v[94:97], v[218:221], v[0:15]
	v_fma_f32 v239, v19, v69, v239
	v_max_i32_e32 v20, 0, v20
	v_max_i32_e32 v21, 0, v21
	v_fma_f32 v238, v20, v70, v238
	v_fma_f32 v239, v21, v71, v239
	v_max_i32_e32 v22, 0, v22
	v_max_i32_e32 v23, 0, v23
	v_mfma_f32_32x32x16_f16 v[0:15], v[98:101], v[222:225], v[0:15]
	v_fma_f32 v238, v22, v72, v238
	v_fma_f32 v239, v23, v73, v239
	v_max_i32_e32 v24, 0, v24
	v_max_i32_e32 v25, 0, v25
	v_fma_f32 v238, v24, v74, v238
	v_fma_f32 v239, v25, v75, v239
	v_mfma_f32_32x32x16_f16 v[0:15], v[102:105], v[226:229], v[0:15]
	v_max_i32_e32 v26, 0, v26
	v_max_i32_e32 v27, 0, v27
	v_fma_f32 v238, v26, v76, v238
	v_fma_f32 v239, v27, v77, v239
	v_max_i32_e32 v28, 0, v28
	v_max_i32_e32 v29, 0, v29
	v_mfma_f32_32x32x16_f16 v[0:15], v[106:109], v[230:233], v[0:15]
	v_fma_f32 v238, v28, v78, v238
	v_fma_f32 v239, v29, v79, v239
	v_max_i32_e32 v30, 0, v30
	v_max_i32_e32 v31, 0, v31
	v_fma_f32 v238, v30, v80, v238
	v_fma_f32 v239, v31, v81, v239
	v_mfma_f32_32x32x16_f16 v[0:15], v[110:113], v[234:237], v[0:15]
	v_add_f32_e32 v240, v238, v239
	v_mov_b32_e32 v241, v240
	v_lshlrev_b32_e32 v242, 2, v32
	s_nop 0
	v_permlane32_swap_b32_e32 v241, v240
	v_add_f32_e32 v241, v241, v240
	s_mov_b64 exec, s[4:5]
	global_store_dword v242, v241, s[24:25]
	s_mov_b64 exec, -1
	s_waitcnt lgkmcnt(0)
; #define LAS __attribute__((address_space(3)))
; DI void indexer_tile(const LAS unsigned char* buf, const f16x8 (&af)[2][8], const f32x4 (&wv)[2][4], float* sc0, float* sc1, int kt, int r32, int h2) {
;     ...
;     for (int sub = 0; sub < 2; ++sub) {
;         f32x16 c0, c1;
; #pragma unroll
;         for (int i = 0; i < 16; ++i) { c0[i] = 0.f; c1[i] = 0.f; }
; #pragma unroll
;         for (int ks = 0; ks < 8; ++ks) { c0 = __builtin_amdgcn_mfma_f32_32x32x16_f16(af[0][ks], bfr[sub][ks], c0, 0, 0, 0); c1 = __builtin_amdgcn_mfma_f32_32x32x16_f16(af[1][ks], bfr[sub][ks], c1, 0, 0, 0); }
;         f32x2_t a0 = {0.f, 0.f}, a1 = {0.f, 0.f};
; #pragma unroll
;         for (int q = 0; q < 4; ++q)
; #pragma unroll
;             for (int e = 0; e < 4; e += 2) {
;                 const f32x2_t r0 = {relu1(c0[4 * q + e]), relu1(c0[4 * q + e + 1])};
;                 const f32x2_t r1 = {relu1(c1[4 * q + e]), relu1(c1[4 * q + e + 1])};
;                 const f32x2_t w0 = {wv[0][q][e], wv[0][q][e + 1]}, w1 = {wv[1][q][e], wv[1][q][e + 1]};
;                 a0 = __builtin_elementwise_fma(r0, w0, a0); a1 = __builtin_elementwise_fma(r1, w1, a1); }
;         float s0 = a0.x + a0.y, s1 = a1.x + a1.y;
;         s0 += __shfl_xor(s0, 32); s1 += __shfl_xor(s1, 32);
;         if (h2 == 0) { sc0[kt * 64 + 32 * sub + r32] = s0; sc1[kt * 64 + 32 * sub + r32] = s1; }
; DI void indexer_phase(const unsigned short* QI, const unsigned short* KI16, const float* WI, float* SC, LAS unsigned char* lds, int tid, int bid, int G) {
;     ...
;                 if (kt + 1 < nt) { *(LAS u32x4*)(buf1 + key0 * KT_ROWB + ch * 16) = b0; *(LAS u32x4*)(buf1 + (key0 + 32) * KT_ROWB + ch * 16) = b1; }
	v_mfma_f32_32x32x16_f16 v[16:31], v[34:37], v[174:177], 0
	v_mfma_f32_32x32x16_f16 v[16:31], v[38:41], v[170:173], v[16:31]
	v_mfma_f32_32x32x16_f16 v[16:31], v[42:45], v[166:169], v[16:31]
	s_nop 8
	v_max_i32_e32 v0, 0, v0
	v_max_i32_e32 v1, 0, v1
	v_fma_f32 v243, v0, v114, 0
	v_fma_f32 v244, v1, v115, 0
	v_max_i32_e32 v2, 0, v2
	v_max_i32_e32 v3, 0, v3
	v_fma_f32 v243, v2, v116, v243
	v_mfma_f32_32x32x16_f16 v[16:31], v[46:49], v[162:165], v[16:31]
	v_fma_f32 v244, v3, v117, v244
	v_max_i32_e32 v4, 0, v4
	v_max_i32_e32 v5, 0, v5
	v_fma_f32 v243, v4, v118, v243
	v_fma_f32 v244, v5, v119, v244
	v_max_i32_e32 v6, 0, v6
	v_max_i32_e32 v7, 0, v7
	v_mfma_f32_32x32x16_f16 v[16:31], v[50:53], v[158:161], v[16:31]
	v_fma_f32 v243, v6, v120, v243
	v_fma_f32 v244, v7, v121, v244
	v_max_i32_e32 v8, 0, v8
	v_max_i32_e32 v9, 0, v9
	v_fma_f32 v243, v8, v122, v243
	v_fma_f32 v244, v9, v123, v244
	v_mfma_f32_32x32x16_f16 v[16:31], v[54:57], v[154:157], v[16:31]
	v_max_i32_e32 v10, 0, v10
	v_max_i32_e32 v11, 0, v11
	v_fma_f32 v243, v10, v124, v243
	v_fma_f32 v244, v11, v125, v244
	v_max_i32_e32 v12, 0, v12
	v_max_i32_e32 v13, 0, v13
	v_mfma_f32_32x32x16_f16 v[16:31], v[58:61], v[150:153], v[16:31]
	v_fma_f32 v243, v12, v126, v243
	v_fma_f32 v244, v13, v127, v244
	v_max_i32_e32 v14, 0, v14
	v_max_i32_e32 v15, 0, v15
	v_fma_f32 v243, v14, v128, v243
	v_fma_f32 v244, v15, v129, v244
	v_mfma_f32_32x32x16_f16 v[16:31], v[62:65], v[146:149], v[16:31]
	v_add_f32_e32 v245, v243, v244
	v_mov_b32_e32 v246, v245
	v_lshlrev_b32_e32 v247, 2, v32
	s_nop 0
	v_permlane32_swap_b32_e32 v246, v245
	v_add_f32_e32 v246, v246, v245
	s_mov_b64 exec, s[4:5]
	global_store_dword v247, v246, s[26:27]
	s_mov_b64 exec, -1
	v_mfma_f32_32x32x16_f16 v[0:15], v[82:85], v[174:177], 0
	v_mfma_f32_32x32x16_f16 v[0:15], v[86:89], v[170:173], v[0:15]
	v_mfma_f32_32x32x16_f16 v[0:15], v[90:93], v[166:169], v[0:15]
	s_nop 8
	v_max_i32_e32 v16, 0, v16
	v_max_i32_e32 v17, 0, v17
	v_fma_f32 v238, v16, v66, 0
	v_fma_f32 v239, v17, v67, 0
	v_max_i32_e32 v18, 0, v18
	v_max_i32_e32 v19, 0, v19
	v_fma_f32 v238, v18, v68, v238
	v_mfma_f32_32x32x16_f16 v[0:15], v[94:97], v[162:165], v[0:15]
	v_fma_f32 v239, v19, v69, v239
	v_max_i32_e32 v20, 0, v20
	v_max_i32_e32 v21, 0, v21
	v_fma_f32 v238, v20, v70, v238
	v_fma_f32 v239, v21, v71, v239
	v_max_i32_e32 v22, 0, v22
	v_max_i32_e32 v23, 0, v23
	v_mfma_f32_32x32x16_f16 v[0:15], v[98:101], v[158:161], v[0:15]
	v_fma_f32 v238, v22, v72, v238
	v_fma_f32 v239, v23, v73, v239
	v_max_i32_e32 v24, 0, v24
	v_max_i32_e32 v25, 0, v25
	v_fma_f32 v238, v24, v74, v238
	v_fma_f32 v239, v25, v75, v239
	v_mfma_f32_32x32x16_f16 v[0:15], v[102:105], v[154:157], v[0:15]
	v_max_i32_e32 v26, 0, v26
	v_max_i32_e32 v27, 0, v27
	v_fma_f32 v238, v26, v76, v238
	v_fma_f32 v239, v27, v77, v239
	v_max_i32_e32 v28, 0, v28
	v_max_i32_e32 v29, 0, v29
	v_mfma_f32_32x32x16_f16 v[0:15], v[106:109], v[150:153], v[0:15]
	v_fma_f32 v238, v28, v78, v238
	v_fma_f32 v239, v29, v79, v239
	v_max_i32_e32 v30, 0, v30
	v_max_i32_e32 v31, 0, v31
	v_fma_f32 v238, v30, v80, v238
	v_fma_f32 v239, v31, v81, v239
	v_mfma_f32_32x32x16_f16 v[0:15], v[110:113], v[146:149], v[0:15]
	v_add_f32_e32 v240, v238, v239
	v_mov_b32_e32 v241, v240
	v_lshlrev_b32_e32 v242, 2, v32
	s_nop 0
	v_permlane32_swap_b32_e32 v241, v240
	v_add_f32_e32 v241, v241, v240
	s_mov_b64 exec, s[4:5]
	global_store_dword v242, v241, s[24:25] offset:128
	s_mov_b64 exec, -1
	s_nop 11
	v_max_i32_e32 v0, 0, v0
	v_max_i32_e32 v1, 0, v1
	v_fma_f32 v243, v0, v114, 0
	v_fma_f32 v244, v1, v115, 0
	v_max_i32_e32 v2, 0, v2
	v_max_i32_e32 v3, 0, v3
	v_fma_f32 v243, v2, v116, v243
	v_fma_f32 v244, v3, v117, v244
	v_max_i32_e32 v4, 0, v4
	v_max_i32_e32 v5, 0, v5
	v_fma_f32 v243, v4, v118, v243
	v_fma_f32 v244, v5, v119, v244
	v_max_i32_e32 v6, 0, v6
	v_max_i32_e32 v7, 0, v7
	v_fma_f32 v243, v6, v120, v243
	v_fma_f32 v244, v7, v121, v244
	v_max_i32_e32 v8, 0, v8
	v_max_i32_e32 v9, 0, v9
	v_fma_f32 v243, v8, v122, v243
	v_fma_f32 v244, v9, v123, v244
	v_max_i32_e32 v10, 0, v10
	v_max_i32_e32 v11, 0, v11
	v_fma_f32 v243, v10, v124, v243
	v_fma_f32 v244, v11, v125, v244
	v_max_i32_e32 v12, 0, v12
	v_max_i32_e32 v13, 0, v13
	v_fma_f32 v243, v12, v126, v243
	v_fma_f32 v244, v13, v127, v244
	v_max_i32_e32 v14, 0, v14
	v_max_i32_e32 v15, 0, v15
	v_fma_f32 v243, v14, v128, v243
	v_fma_f32 v244, v15, v129, v244
	v_add_f32_e32 v245, v243, v244
	v_mov_b32_e32 v246, v245
	v_lshlrev_b32_e32 v247, 2, v32
	s_nop 0
	v_permlane32_swap_b32_e32 v246, v245
	v_add_f32_e32 v246, v246, v245
	s_mov_b64 exec, s[4:5]
	global_store_dword v247, v246, s[26:27] offset:128
	s_mov_b64 exec, -1
	s_add_i32 s47, s11, -3
	s_cmp_lt_u32 s47, s42
	s_cselect_b64 s[30:31], -1, 0
	s_cmp_ge_u32 s47, s42
	s_cbranch_scc1 .LBB0_1853
	s_waitcnt vmcnt(8)
	ds_write_b128 v209, v[134:137] offset:17408
	ds_write_b128 v209, v[142:145] offset:26112

; #define LAS __attribute__((address_space(3)))
; DI void indexer_tile(const LAS unsigned char* buf, const f16x8 (&af)[2][8], const f32x4 (&wv)[2][4], float* sc0, float* sc1, int kt, int r32, int h2) {
;     ...
;         for (int ks = 0; ks < 8; ++ks) bfr[sub][ks] = *(const LAS f16x8*)(buf + (32 * sub + r32) * KT_ROWB + (16 * ks + 8 * h2) * 2);
;     __builtin_amdgcn_sched_barrier(0);
; #pragma unroll
;     for (int sub = 0; sub < 2; ++sub) {
;         f32x16 c0, c1;
; #pragma unroll
;         for (int i = 0; i < 16; ++i) { c0[i] = 0.f; c1[i] = 0.f; }
; #pragma unroll
;         for (int ks = 0; ks < 8; ++ks) { c0 = __builtin_amdgcn_mfma_f32_32x32x16_f16(af[0][ks], bfr[sub][ks], c0, 0, 0, 0); c1 = __builtin_amdgcn_mfma_f32_32x32x16_f16(af[1][ks], bfr[sub][ks], c1, 0, 0, 0); }
;         f32x2_t a0 = {0.f, 0.f}, a1 = {0.f, 0.f};
; #pragma unroll
;         for (int q = 0; q < 4; ++q)
; #pragma unroll
;             for (int e = 0; e < 4; e += 2) {
;                 const f32x2_t r0 = {relu1(c0[4 * q + e]), relu1(c0[4 * q + e + 1])};
;                 const f32x2_t r1 = {relu1(c1[4 * q + e]), relu1(c1[4 * q + e + 1])};
;                 const f32x2_t w0 = {wv[0][q][e], wv[0][q][e + 1]}, w1 = {wv[1][q][e], wv[1][q][e + 1]};
;                 a0 = __builtin_elementwise_fma(r0, w0, a0); a1 = __builtin_elementwise_fma(r1, w1, a1); }
;         float s0 = a0.x + a0.y, s1 = a1.x + a1.y;
;         s0 += __shfl_xor(s0, 32); s1 += __shfl_xor(s1, 32);
;         if (h2 == 0) { sc0[kt * 64 + 32 * sub + r32] = s0; sc1[kt * 64 + 32 * sub + r32] = s1; }
.LBB0_1856:
	ds_read_b128 v[0:3], v207 offset:17408
	ds_read_b128 v[210:213], v207 offset:17440
	ds_read_b128 v[214:217], v207 offset:17472
	ds_read_b128 v[218:221], v207 offset:17504
	ds_read_b128 v[222:225], v207 offset:17536
	ds_read_b128 v[226:229], v207 offset:17568
	ds_read_b128 v[230:233], v207 offset:17600
	ds_read_b128 v[234:237], v207 offset:17632
	ds_read_b128 v[174:177], v207 offset:26112
	ds_read_b128 v[170:173], v207 offset:26144
	ds_read_b128 v[166:169], v207 offset:26176
	ds_read_b128 v[162:165], v207 offset:26208
	ds_read_b128 v[158:161], v207 offset:26240
	ds_read_b128 v[154:157], v207 offset:26272
	ds_read_b128 v[150:153], v207 offset:26304
	ds_read_b128 v[146:149], v207 offset:26336
	s_waitcnt lgkmcnt(15)
	v_mfma_f32_32x32x16_f16 v[16:31], v[34:37], v[0:3], 0
	s_waitcnt lgkmcnt(14)
	v_mfma_f32_32x32x16_f16 v[16:31], v[38:41], v[210:213], v[16:31]
	s_waitcnt lgkmcnt(13)
	v_mfma_f32_32x32x16_f16 v[16:31], v[42:45], v[214:217], v[16:31]
	s_waitcnt lgkmcnt(12)
	v_mfma_f32_32x32x16_f16 v[16:31], v[46:49], v[218:221], v[16:31]
	s_waitcnt lgkmcnt(11)
	v_mfma_f32_32x32x16_f16 v[16:31], v[50:53], v[222:225], v[16:31]
	s_waitcnt lgkmcnt(10)
	v_mfma_f32_32x32x16_f16 v[16:31], v[54:57], v[226:229], v[16:31]
	s_waitcnt lgkmcnt(9)
	v_mfma_f32_32x32x16_f16 v[16:31], v[58:61], v[230:233], v[16:31]
	s_waitcnt lgkmcnt(8)
	v_mfma_f32_32x32x16_f16 v[16:31], v[62:65], v[234:237], v[16:31]
	v_mfma_f32_32x32x16_f16 v[0:15], v[82:85], v[0:3], 0
	v_mfma_f32_32x32x16_f16 v[0:15], v[86:89], v[210:213], v[0:15]
	v_mfma_f32_32x32x16_f16 v[0:15], v[90:93], v[214:217], v[0:15]
	s_nop 8
	v_max_i32_e32 v16, 0, v16
	v_max_i32_e32 v17, 0, v17
	v_fma_f32 v238, v16, v66, 0
	v_fma_f32 v239, v17, v67, 0
	v_max_i32_e32 v18, 0, v18
	v_max_i32_e32 v19, 0, v19
	v_fma_f32 v238, v18, v68, v238
	v_mfma_f32_32x32x16_f16 v[0:15], v[94:97], v[218:221], v[0:15]
	v_fma_f32 v239, v19, v69, v239
	v_max_i32_e32 v20, 0, v20
	v_max_i32_e32 v21, 0, v21
	v_fma_f32 v238, v20, v70, v238
	v_fma_f32 v239, v21, v71, v239
	v_max_i32_e32 v22, 0, v22
	v_max_i32_e32 v23, 0, v23
	v_mfma_f32_32x32x16_f16 v[0:15], v[98:101], v[222:225], v[0:15]
	v_fma_f32 v238, v22, v72, v238
	v_fma_f32 v239, v23, v73, v239
	v_max_i32_e32 v24, 0, v24
	v_max_i32_e32 v25, 0, v25
	v_fma_f32 v238, v24, v74, v238
	v_fma_f32 v239, v25, v75, v239
	v_mfma_f32_32x32x16_f16 v[0:15], v[102:105], v[226:229], v[0:15]
	v_max_i32_e32 v26, 0, v26
	v_max_i32_e32 v27, 0, v27
	v_fma_f32 v238, v26, v76, v238
	v_fma_f32 v239, v27, v77, v239
	v_max_i32_e32 v28, 0, v28
	v_max_i32_e32 v29, 0, v29
	v_mfma_f32_32x32x16_f16 v[0:15], v[106:109], v[230:233], v[0:15]
	v_fma_f32 v238, v28, v78, v238
	v_fma_f32 v239, v29, v79, v239
	v_max_i32_e32 v30, 0, v30
	v_max_i32_e32 v31, 0, v31
	v_fma_f32 v238, v30, v80, v238
	v_fma_f32 v239, v31, v81, v239
	v_mfma_f32_32x32x16_f16 v[0:15], v[110:113], v[234:237], v[0:15]
	v_add_f32_e32 v240, v238, v239
	v_mov_b32_e32 v241, v240
	v_lshlrev_b32_e32 v242, 2, v32
	s_nop 0
	v_permlane32_swap_b32_e32 v241, v240
	v_add_f32_e32 v241, v241, v240
	s_mov_b64 exec, s[4:5]
	global_store_dword v242, v241, s[24:25] offset:256
	s_mov_b64 exec, -1
	s_waitcnt lgkmcnt(0)
; #define LAS __attribute__((address_space(3)))
; DI void indexer_tile(const LAS unsigned char* buf, const f16x8 (&af)[2][8], const f32x4 (&wv)[2][4], float* sc0, float* sc1, int kt, int r32, int h2) {
;     ...
;     for (int sub = 0; sub < 2; ++sub) {
;         f32x16 c0, c1;
; #pragma unroll
;         for (int i = 0; i < 16; ++i) { c0[i] = 0.f; c1[i] = 0.f; }
; #pragma unroll
;         for (int ks = 0; ks < 8; ++ks) { c0 = __builtin_amdgcn_mfma_f32_32x32x16_f16(af[0][ks], bfr[sub][ks], c0, 0, 0, 0); c1 = __builtin_amdgcn_mfma_f32_32x32x16_f16(af[1][ks], bfr[sub][ks], c1, 0, 0, 0); }
;         f32x2_t a0 = {0.f, 0.f}, a1 = {0.f, 0.f};
; #pragma unroll
;         for (int q = 0; q < 4; ++q)
; #pragma unroll
;             for (int e = 0; e < 4; e += 2) {
;                 const f32x2_t r0 = {relu1(c0[4 * q + e]), relu1(c0[4 * q + e + 1])};
;                 const f32x2_t r1 = {relu1(c1[4 * q + e]), relu1(c1[4 * q + e + 1])};
;                 const f32x2_t w0 = {wv[0][q][e], wv[0][q][e + 1]}, w1 = {wv[1][q][e], wv[1][q][e + 1]};
;                 a0 = __builtin_elementwise_fma(r0, w0, a0); a1 = __builtin_elementwise_fma(r1, w1, a1); }
;         float s0 = a0.x + a0.y, s1 = a1.x + a1.y;
;         s0 += __shfl_xor(s0, 32); s1 += __shfl_xor(s1, 32);
;         if (h2 == 0) { sc0[kt * 64 + 32 * sub + r32] = s0; sc1[kt * 64 + 32 * sub + r32] = s1; }
; DI void indexer_phase(const unsigned short* QI, const unsigned short* KI16, const float* WI, float* SC, LAS unsigned char* lds, int tid, int bid, int G) {
;     ...
;                 if (kt + 2 < nt) { *(LAS u32x4*)(buf0 + key0 * KT_ROWB + ch * 16) = a0; *(LAS u32x4*)(buf0 + (key0 + 32) * KT_ROWB + ch * 16) = a1; }
	v_mfma_f32_32x32x16_f16 v[16:31], v[34:37], v[174:177], 0
	v_mfma_f32_32x32x16_f16 v[16:31], v[38:41], v[170:173], v[16:31]
	v_mfma_f32_32x32x16_f16 v[16:31], v[42:45], v[166:169], v[16:31]
	s_nop 8
	v_max_i32_e32 v0, 0, v0
	v_max_i32_e32 v1, 0, v1
	v_fma_f32 v243, v0, v114, 0
	v_fma_f32 v244, v1, v115, 0
	v_max_i32_e32 v2, 0, v2
	v_max_i32_e32 v3, 0, v3
	v_fma_f32 v243, v2, v116, v243
	v_mfma_f32_32x32x16_f16 v[16:31], v[46:49], v[162:165], v[16:31]
	v_fma_f32 v244, v3, v117, v244
	v_max_i32_e32 v4, 0, v4
	v_max_i32_e32 v5, 0, v5
	v_fma_f32 v243, v4, v118, v243
	v_fma_f32 v244, v5, v119, v244
	v_max_i32_e32 v6, 0, v6
	v_max_i32_e32 v7, 0, v7
	v_mfma_f32_32x32x16_f16 v[16:31], v[50:53], v[158:161], v[16:31]
	v_fma_f32 v243, v6, v120, v243
	v_fma_f32 v244, v7, v121, v244
	v_max_i32_e32 v8, 0, v8
	v_max_i32_e32 v9, 0, v9
	v_fma_f32 v243, v8, v122, v243
	v_fma_f32 v244, v9, v123, v244
	v_mfma_f32_32x32x16_f16 v[16:31], v[54:57], v[154:157], v[16:31]
	v_max_i32_e32 v10, 0, v10
	v_max_i32_e32 v11, 0, v11
	v_fma_f32 v243, v10, v124, v243
	v_fma_f32 v244, v11, v125, v244
	v_max_i32_e32 v12, 0, v12
	v_max_i32_e32 v13, 0, v13
	v_mfma_f32_32x32x16_f16 v[16:31], v[58:61], v[150:153], v[16:31]
	v_fma_f32 v243, v12, v126, v243
	v_fma_f32 v244, v13, v127, v244
	v_max_i32_e32 v14, 0, v14
	v_max_i32_e32 v15, 0, v15
	v_fma_f32 v243, v14, v128, v243
	v_fma_f32 v244, v15, v129, v244
	v_mfma_f32_32x32x16_f16 v[16:31], v[62:65], v[146:149], v[16:31]
	v_add_f32_e32 v245, v243, v244
	v_mov_b32_e32 v246, v245
	v_lshlrev_b32_e32 v247, 2, v32
	s_nop 0
	v_permlane32_swap_b32_e32 v246, v245
	v_add_f32_e32 v246, v246, v245
	s_mov_b64 exec, s[4:5]
	global_store_dword v247, v246, s[26:27] offset:256
	s_mov_b64 exec, -1
	v_mfma_f32_32x32x16_f16 v[0:15], v[82:85], v[174:177], 0
	v_mfma_f32_32x32x16_f16 v[0:15], v[86:89], v[170:173], v[0:15]
	v_mfma_f32_32x32x16_f16 v[0:15], v[90:93], v[166:169], v[0:15]
	s_nop 8
	v_max_i32_e32 v16, 0, v16
	v_max_i32_e32 v17, 0, v17
	v_fma_f32 v238, v16, v66, 0
	v_fma_f32 v239, v17, v67, 0
	v_max_i32_e32 v18, 0, v18
	v_max_i32_e32 v19, 0, v19
	v_fma_f32 v238, v18, v68, v238
	v_mfma_f32_32x32x16_f16 v[0:15], v[94:97], v[162:165], v[0:15]
	v_fma_f32 v239, v19, v69, v239
	v_max_i32_e32 v20, 0, v20
	v_max_i32_e32 v21, 0, v21
	v_fma_f32 v238, v20, v70, v238
	v_fma_f32 v239, v21, v71, v239
	v_max_i32_e32 v22, 0, v22
	v_max_i32_e32 v23, 0, v23
	v_mfma_f32_32x32x16_f16 v[0:15], v[98:101], v[158:161], v[0:15]
	v_fma_f32 v238, v22, v72, v238
	v_fma_f32 v239, v23, v73, v239
	v_max_i32_e32 v24, 0, v24
	v_max_i32_e32 v25, 0, v25
	v_fma_f32 v238, v24, v74, v238
	v_fma_f32 v239, v25, v75, v239
	v_mfma_f32_32x32x16_f16 v[0:15], v[102:105], v[154:157], v[0:15]
	v_max_i32_e32 v26, 0, v26
	v_max_i32_e32 v27, 0, v27
	v_fma_f32 v238, v26, v76, v238
	v_fma_f32 v239, v27, v77, v239
	v_max_i32_e32 v28, 0, v28
	v_max_i32_e32 v29, 0, v29
	v_mfma_f32_32x32x16_f16 v[0:15], v[106:109], v[150:153], v[0:15]
	v_fma_f32 v238, v28, v78, v238
	v_fma_f32 v239, v29, v79, v239
	v_max_i32_e32 v30, 0, v30
	v_max_i32_e32 v31, 0, v31
	v_fma_f32 v238, v30, v80, v238
	v_fma_f32 v239, v31, v81, v239
	v_mfma_f32_32x32x16_f16 v[0:15], v[110:113], v[146:149], v[0:15]
	v_add_f32_e32 v240, v238, v239
	v_mov_b32_e32 v241, v240
	v_lshlrev_b32_e32 v242, 2, v32
	s_nop 0
	v_permlane32_swap_b32_e32 v241, v240
	v_add_f32_e32 v241, v241, v240
	s_mov_b64 exec, s[4:5]
	global_store_dword v242, v241, s[24:25] offset:384
	s_mov_b64 exec, -1
	s_nop 11
	v_max_i32_e32 v0, 0, v0
	v_max_i32_e32 v1, 0, v1
	v_fma_f32 v243, v0, v114, 0
	v_fma_f32 v244, v1, v115, 0
	v_max_i32_e32 v2, 0, v2
	v_max_i32_e32 v3, 0, v3
	v_fma_f32 v243, v2, v116, v243
	v_fma_f32 v244, v3, v117, v244
	v_max_i32_e32 v4, 0, v4
	v_max_i32_e32 v5, 0, v5
	v_fma_f32 v243, v4, v118, v243
	v_fma_f32 v244, v5, v119, v244
	v_max_i32_e32 v6, 0, v6
	v_max_i32_e32 v7, 0, v7
	v_fma_f32 v243, v6, v120, v243
	v_fma_f32 v244, v7, v121, v244
	v_max_i32_e32 v8, 0, v8
	v_max_i32_e32 v9, 0, v9
	v_fma_f32 v243, v8, v122, v243
	v_fma_f32 v244, v9, v123, v244
	v_max_i32_e32 v10, 0, v10
	v_max_i32_e32 v11, 0, v11
	v_fma_f32 v243, v10, v124, v243
	v_fma_f32 v244, v11, v125, v244
	v_max_i32_e32 v12, 0, v12
	v_max_i32_e32 v13, 0, v13
	v_fma_f32 v243, v12, v126, v243
	v_fma_f32 v244, v13, v127, v244
	v_max_i32_e32 v14, 0, v14
	v_max_i32_e32 v15, 0, v15
	v_fma_f32 v243, v14, v128, v243
	v_fma_f32 v244, v15, v129, v244
	v_add_f32_e32 v245, v243, v244
	v_mov_b32_e32 v246, v245
	v_lshlrev_b32_e32 v247, 2, v32
	s_nop 0
	v_permlane32_swap_b32_e32 v246, v245
	v_add_f32_e32 v246, v246, v245
	s_mov_b64 exec, s[4:5]
	global_store_dword v247, v246, s[26:27] offset:384
	s_mov_b64 exec, -1
	s_andn2_b64 vcc, exec, s[28:29]
	s_cbranch_vccnz .LBB0_1844
	s_waitcnt vmcnt(8)
	ds_write_b128 v209, v[130:133]
	ds_write_b128 v209, v[138:141] offset:8704
	s_branch .LBB0_1844

; #define LAS __attribute__((address_space(3)))
; DI void indexer_tile(const LAS unsigned char* buf, const f16x8 (&af)[2][8], const f32x4 (&wv)[2][4], float* sc0, float* sc1, int kt, int r32, int h2) {
;     ...
;         for (int ks = 0; ks < 8; ++ks) bfr[sub][ks] = *(const LAS f16x8*)(buf + (32 * sub + r32) * KT_ROWB + (16 * ks + 8 * h2) * 2);
;     __builtin_amdgcn_sched_barrier(0);
; #pragma unroll
;     for (int sub = 0; sub < 2; ++sub) {
;         f32x16 c0, c1;
; #pragma unroll
;         for (int i = 0; i < 16; ++i) { c0[i] = 0.f; c1[i] = 0.f; }
; #pragma unroll
;         for (int ks = 0; ks < 8; ++ks) { c0 = __builtin_amdgcn_mfma_f32_32x32x16_f16(af[0][ks], bfr[sub][ks], c0, 0, 0, 0); c1 = __builtin_amdgcn_mfma_f32_32x32x16_f16(af[1][ks], bfr[sub][ks], c1, 0, 0, 0); }
;         f32x2_t a0 = {0.f, 0.f}, a1 = {0.f, 0.f};
; #pragma unroll
;         for (int q = 0; q < 4; ++q)
; #pragma unroll
;             for (int e = 0; e < 4; e += 2) {
;                 const f32x2_t r0 = {relu1(c0[4 * q + e]), relu1(c0[4 * q + e + 1])};
;                 const f32x2_t r1 = {relu1(c1[4 * q + e]), relu1(c1[4 * q + e + 1])};
;                 const f32x2_t w0 = {wv[0][q][e], wv[0][q][e + 1]}, w1 = {wv[1][q][e], wv[1][q][e + 1]};
;                 a0 = __builtin_elementwise_fma(r0, w0, a0); a1 = __builtin_elementwise_fma(r1, w1, a1); }
;         float s0 = a0.x + a0.y, s1 = a1.x + a1.y;
;         s0 += __shfl_xor(s0, 32); s1 += __shfl_xor(s1, 32);
;         if (h2 == 0) { sc0[kt * 64 + 32 * sub + r32] = s0; sc1[kt * 64 + 32 * sub + r32] = s1; }
.LBB0_1871:
	ds_read_b128 v[0:3], v207
	ds_read_b128 v[210:213], v207 offset:32
	ds_read_b128 v[214:217], v207 offset:64
	ds_read_b128 v[218:221], v207 offset:96
	ds_read_b128 v[222:225], v207 offset:128
	ds_read_b128 v[226:229], v207 offset:160
	ds_read_b128 v[230:233], v207 offset:192
	ds_read_b128 v[234:237], v207 offset:224
	ds_read_b128 v[176:179], v207 offset:8704
	ds_read_b128 v[172:175], v207 offset:8736
	ds_read_b128 v[168:171], v207 offset:8768
	ds_read_b128 v[164:167], v207 offset:8800
	ds_read_b128 v[160:163], v207 offset:8832
	ds_read_b128 v[156:159], v207 offset:8864
	ds_read_b128 v[152:155], v207 offset:8896
	ds_read_b128 v[148:151], v207 offset:8928
	s_waitcnt lgkmcnt(15)
	v_mfma_f32_32x32x16_f16 v[16:31], v[36:39], v[0:3], 0
	s_waitcnt lgkmcnt(14)
	v_mfma_f32_32x32x16_f16 v[16:31], v[40:43], v[210:213], v[16:31]
	s_waitcnt lgkmcnt(13)
	v_mfma_f32_32x32x16_f16 v[16:31], v[44:47], v[214:217], v[16:31]
	s_waitcnt lgkmcnt(12)
	v_mfma_f32_32x32x16_f16 v[16:31], v[48:51], v[218:221], v[16:31]
	s_waitcnt lgkmcnt(11)
	v_mfma_f32_32x32x16_f16 v[16:31], v[52:55], v[222:225], v[16:31]
	s_waitcnt lgkmcnt(10)
	v_mfma_f32_32x32x16_f16 v[16:31], v[56:59], v[226:229], v[16:31]
	s_waitcnt lgkmcnt(9)
	v_mfma_f32_32x32x16_f16 v[16:31], v[60:63], v[230:233], v[16:31]
	s_waitcnt lgkmcnt(8)
	v_mfma_f32_32x32x16_f16 v[16:31], v[64:67], v[234:237], v[16:31]
	v_mfma_f32_32x32x16_f16 v[0:15], v[84:87], v[0:3], 0
	v_mfma_f32_32x32x16_f16 v[0:15], v[88:91], v[210:213], v[0:15]
	v_mfma_f32_32x32x16_f16 v[0:15], v[92:95], v[214:217], v[0:15]
	s_nop 8
	v_max_i32_e32 v16, 0, v16
	v_max_i32_e32 v17, 0, v17
	v_fma_f32 v238, v16, v68, 0
	v_fma_f32 v239, v17, v69, 0
	v_max_i32_e32 v18, 0, v18
	v_max_i32_e32 v19, 0, v19
	v_fma_f32 v238, v18, v70, v238
	v_mfma_f32_32x32x16_f16 v[0:15], v[96:99], v[218:221], v[0:15]
	v_fma_f32 v239, v19, v71, v239
	v_max_i32_e32 v20, 0, v20
	v_max_i32_e32 v21, 0, v21
	v_fma_f32 v238, v20, v72, v238
	v_fma_f32 v239, v21, v73, v239
	v_max_i32_e32 v22, 0, v22
	v_max_i32_e32 v23, 0, v23
	v_mfma_f32_32x32x16_f16 v[0:15], v[100:103], v[222:225], v[0:15]
	v_fma_f32 v238, v22, v74, v238
	v_fma_f32 v239, v23, v75, v239
	v_max_i32_e32 v24, 0, v24
	v_max_i32_e32 v25, 0, v25
	v_fma_f32 v238, v24, v76, v238
	v_fma_f32 v239, v25, v77, v239
	v_mfma_f32_32x32x16_f16 v[0:15], v[104:107], v[226:229], v[0:15]
	v_max_i32_e32 v26, 0, v26
	v_max_i32_e32 v27, 0, v27
	v_fma_f32 v238, v26, v78, v238
	v_fma_f32 v239, v27, v79, v239
	v_max_i32_e32 v28, 0, v28
	v_max_i32_e32 v29, 0, v29
	v_mfma_f32_32x32x16_f16 v[0:15], v[108:111], v[230:233], v[0:15]
	v_fma_f32 v238, v28, v80, v238
	v_fma_f32 v239, v29, v81, v239
	v_max_i32_e32 v30, 0, v30
	v_max_i32_e32 v31, 0, v31
	v_fma_f32 v238, v30, v82, v238
	v_fma_f32 v239, v31, v83, v239
	v_mfma_f32_32x32x16_f16 v[0:15], v[112:115], v[234:237], v[0:15]
	v_add_f32_e32 v240, v238, v239
	v_mov_b32_e32 v241, v240
	v_lshlrev_b32_e32 v242, 2, v32
	s_nop 0
	v_permlane32_swap_b32_e32 v241, v240
	v_add_f32_e32 v241, v241, v240
	s_mov_b64 exec, s[4:5]
	global_store_dword v242, v241, s[6:7]
	s_mov_b64 exec, -1
	s_waitcnt lgkmcnt(0)
; #define LAS __attribute__((address_space(3)))
; DI void indexer_tile(const LAS unsigned char* buf, const f16x8 (&af)[2][8], const f32x4 (&wv)[2][4], float* sc0, float* sc1, int kt, int r32, int h2) {
;     ...
;     for (int sub = 0; sub < 2; ++sub) {
;         f32x16 c0, c1;
; #pragma unroll
;         for (int i = 0; i < 16; ++i) { c0[i] = 0.f; c1[i] = 0.f; }
; #pragma unroll
;         for (int ks = 0; ks < 8; ++ks) { c0 = __builtin_amdgcn_mfma_f32_32x32x16_f16(af[0][ks], bfr[sub][ks], c0, 0, 0, 0); c1 = __builtin_amdgcn_mfma_f32_32x32x16_f16(af[1][ks], bfr[sub][ks], c1, 0, 0, 0); }
;         f32x2_t a0 = {0.f, 0.f}, a1 = {0.f, 0.f};
; #pragma unroll
;         for (int q = 0; q < 4; ++q)
; #pragma unroll
;             for (int e = 0; e < 4; e += 2) {
;                 const f32x2_t r0 = {relu1(c0[4 * q + e]), relu1(c0[4 * q + e + 1])};
;                 const f32x2_t r1 = {relu1(c1[4 * q + e]), relu1(c1[4 * q + e + 1])};
;                 const f32x2_t w0 = {wv[0][q][e], wv[0][q][e + 1]}, w1 = {wv[1][q][e], wv[1][q][e + 1]};
;                 a0 = __builtin_elementwise_fma(r0, w0, a0); a1 = __builtin_elementwise_fma(r1, w1, a1); }
;         float s0 = a0.x + a0.y, s1 = a1.x + a1.y;
;         s0 += __shfl_xor(s0, 32); s1 += __shfl_xor(s1, 32);
;         if (h2 == 0) { sc0[kt * 64 + 32 * sub + r32] = s0; sc1[kt * 64 + 32 * sub + r32] = s1; }
; DI void indexer_phase(const unsigned short* QI, const unsigned short* KI16, const float* WI, float* SC, LAS unsigned char* lds, int tid, int bid, int G) {
;     ...
;                 if (kt + 1 < nt) { *(LAS u32x4*)(buf1 + key0 * KT_ROWB + ch * 16) = b0; *(LAS u32x4*)(buf1 + (key0 + 32) * KT_ROWB + ch * 16) = b1; }
	v_mfma_f32_32x32x16_f16 v[16:31], v[36:39], v[176:179], 0
	v_mfma_f32_32x32x16_f16 v[16:31], v[40:43], v[172:175], v[16:31]
	v_mfma_f32_32x32x16_f16 v[16:31], v[44:47], v[168:171], v[16:31]
	s_nop 8
	v_max_i32_e32 v0, 0, v0
	v_max_i32_e32 v1, 0, v1
	v_fma_f32 v243, v0, v116, 0
	v_fma_f32 v244, v1, v117, 0
	v_max_i32_e32 v2, 0, v2
	v_max_i32_e32 v3, 0, v3
	v_fma_f32 v243, v2, v118, v243
	v_mfma_f32_32x32x16_f16 v[16:31], v[48:51], v[164:167], v[16:31]
	v_fma_f32 v244, v3, v119, v244
	v_max_i32_e32 v4, 0, v4
	v_max_i32_e32 v5, 0, v5
	v_fma_f32 v243, v4, v120, v243
	v_fma_f32 v244, v5, v121, v244
	v_max_i32_e32 v6, 0, v6
	v_max_i32_e32 v7, 0, v7
	v_mfma_f32_32x32x16_f16 v[16:31], v[52:55], v[160:163], v[16:31]
	v_fma_f32 v243, v6, v122, v243
	v_fma_f32 v244, v7, v123, v244
	v_max_i32_e32 v8, 0, v8
	v_max_i32_e32 v9, 0, v9
	v_fma_f32 v243, v8, v124, v243
	v_fma_f32 v244, v9, v125, v244
	v_mfma_f32_32x32x16_f16 v[16:31], v[56:59], v[156:159], v[16:31]
	v_max_i32_e32 v10, 0, v10
	v_max_i32_e32 v11, 0, v11
	v_fma_f32 v243, v10, v126, v243
	v_fma_f32 v244, v11, v127, v244
	v_max_i32_e32 v12, 0, v12
	v_max_i32_e32 v13, 0, v13
	v_mfma_f32_32x32x16_f16 v[16:31], v[60:63], v[152:155], v[16:31]
	v_fma_f32 v243, v12, v128, v243
	v_fma_f32 v244, v13, v129, v244
	v_max_i32_e32 v14, 0, v14
	v_max_i32_e32 v15, 0, v15
	v_fma_f32 v243, v14, v130, v243
	v_fma_f32 v244, v15, v131, v244
	v_mfma_f32_32x32x16_f16 v[16:31], v[64:67], v[148:151], v[16:31]
	v_add_f32_e32 v245, v243, v244
	v_mov_b32_e32 v246, v245
	v_lshlrev_b32_e32 v247, 2, v32
	s_nop 0
	v_permlane32_swap_b32_e32 v246, v245
	v_add_f32_e32 v246, v246, v245
	s_mov_b64 exec, s[4:5]
	global_store_dword v247, v246, s[8:9]
	s_mov_b64 exec, -1
	v_mfma_f32_32x32x16_f16 v[0:15], v[84:87], v[176:179], 0
	v_mfma_f32_32x32x16_f16 v[0:15], v[88:91], v[172:175], v[0:15]
	v_mfma_f32_32x32x16_f16 v[0:15], v[92:95], v[168:171], v[0:15]
	s_nop 8
	v_max_i32_e32 v16, 0, v16
	v_max_i32_e32 v17, 0, v17
	v_fma_f32 v238, v16, v68, 0
	v_fma_f32 v239, v17, v69, 0
	v_max_i32_e32 v18, 0, v18
	v_max_i32_e32 v19, 0, v19
	v_fma_f32 v238, v18, v70, v238
	v_mfma_f32_32x32x16_f16 v[0:15], v[96:99], v[164:167], v[0:15]
	v_fma_f32 v239, v19, v71, v239
	v_max_i32_e32 v20, 0, v20
	v_max_i32_e32 v21, 0, v21
	v_fma_f32 v238, v20, v72, v238
	v_fma_f32 v239, v21, v73, v239
	v_max_i32_e32 v22, 0, v22
	v_max_i32_e32 v23, 0, v23
	v_mfma_f32_32x32x16_f16 v[0:15], v[100:103], v[160:163], v[0:15]
	v_fma_f32 v238, v22, v74, v238
	v_fma_f32 v239, v23, v75, v239
	v_max_i32_e32 v24, 0, v24
	v_max_i32_e32 v25, 0, v25
	v_fma_f32 v238, v24, v76, v238
	v_fma_f32 v239, v25, v77, v239
	v_mfma_f32_32x32x16_f16 v[0:15], v[104:107], v[156:159], v[0:15]
	v_max_i32_e32 v26, 0, v26
	v_max_i32_e32 v27, 0, v27
	v_fma_f32 v238, v26, v78, v238
	v_fma_f32 v239, v27, v79, v239
	v_max_i32_e32 v28, 0, v28
	v_max_i32_e32 v29, 0, v29
	v_mfma_f32_32x32x16_f16 v[0:15], v[108:111], v[152:155], v[0:15]
	v_fma_f32 v238, v28, v80, v238
	v_fma_f32 v239, v29, v81, v239
	v_max_i32_e32 v30, 0, v30
	v_max_i32_e32 v31, 0, v31
	v_fma_f32 v238, v30, v82, v238
	v_fma_f32 v239, v31, v83, v239
	v_mfma_f32_32x32x16_f16 v[0:15], v[112:115], v[148:151], v[0:15]
	v_add_f32_e32 v240, v238, v239
	v_mov_b32_e32 v241, v240
	v_lshlrev_b32_e32 v242, 2, v32
	s_nop 0
	v_permlane32_swap_b32_e32 v241, v240
	v_add_f32_e32 v241, v241, v240
	s_mov_b64 exec, s[4:5]
	global_store_dword v242, v241, s[6:7] offset:128
	s_mov_b64 exec, -1
	s_nop 11
	v_max_i32_e32 v0, 0, v0
	v_max_i32_e32 v1, 0, v1
	v_fma_f32 v243, v0, v116, 0
	v_fma_f32 v244, v1, v117, 0
	v_max_i32_e32 v2, 0, v2
	v_max_i32_e32 v3, 0, v3
	v_fma_f32 v243, v2, v118, v243
	v_fma_f32 v244, v3, v119, v244
	v_max_i32_e32 v4, 0, v4
	v_max_i32_e32 v5, 0, v5
	v_fma_f32 v243, v4, v120, v243
	v_fma_f32 v244, v5, v121, v244
	v_max_i32_e32 v6, 0, v6
	v_max_i32_e32 v7, 0, v7
	v_fma_f32 v243, v6, v122, v243
	v_fma_f32 v244, v7, v123, v244
	v_max_i32_e32 v8, 0, v8
	v_max_i32_e32 v9, 0, v9
	v_fma_f32 v243, v8, v124, v243
	v_fma_f32 v244, v9, v125, v244
	v_max_i32_e32 v10, 0, v10
	v_max_i32_e32 v11, 0, v11
	v_fma_f32 v243, v10, v126, v243
	v_fma_f32 v244, v11, v127, v244
	v_max_i32_e32 v12, 0, v12
	v_max_i32_e32 v13, 0, v13
	v_fma_f32 v243, v12, v128, v243
	v_fma_f32 v244, v13, v129, v244
	v_max_i32_e32 v14, 0, v14
	v_max_i32_e32 v15, 0, v15
	v_fma_f32 v243, v14, v130, v243
	v_fma_f32 v244, v15, v131, v244
	v_add_f32_e32 v245, v243, v244
	v_mov_b32_e32 v246, v245
	v_lshlrev_b32_e32 v247, 2, v32
	s_nop 0
	v_permlane32_swap_b32_e32 v246, v245
	v_add_f32_e32 v246, v246, v245
	s_mov_b64 exec, s[4:5]
	global_store_dword v247, v246, s[8:9] offset:128
	s_mov_b64 exec, -1
	s_add_i32 s24, s14, -3
	s_cmp_lt_i32 s24, s41
	s_cselect_b64 s[12:13], -1, 0
	s_cmp_ge_i32 s24, s41
	s_cbranch_scc1 .LBB0_1877
	s_waitcnt vmcnt(8)
	ds_write_b128 v209, v[140:143] offset:17408
	ds_write_b128 v209, v[144:147] offset:26112

; #define LAS __attribute__((address_space(3)))
; DI void indexer_tile(const LAS unsigned char* buf, const f16x8 (&af)[2][8], const f32x4 (&wv)[2][4], float* sc0, float* sc1, int kt, int r32, int h2) {
;     ...
;         for (int ks = 0; ks < 8; ++ks) bfr[sub][ks] = *(const LAS f16x8*)(buf + (32 * sub + r32) * KT_ROWB + (16 * ks + 8 * h2) * 2);
;     __builtin_amdgcn_sched_barrier(0);
; #pragma unroll
;     for (int sub = 0; sub < 2; ++sub) {
;         f32x16 c0, c1;
; #pragma unroll
;         for (int i = 0; i < 16; ++i) { c0[i] = 0.f; c1[i] = 0.f; }
; #pragma unroll
;         for (int ks = 0; ks < 8; ++ks) { c0 = __builtin_amdgcn_mfma_f32_32x32x16_f16(af[0][ks], bfr[sub][ks], c0, 0, 0, 0); c1 = __builtin_amdgcn_mfma_f32_32x32x16_f16(af[1][ks], bfr[sub][ks], c1, 0, 0, 0); }
;         f32x2_t a0 = {0.f, 0.f}, a1 = {0.f, 0.f};
; #pragma unroll
;         for (int q = 0; q < 4; ++q)
; #pragma unroll
;             for (int e = 0; e < 4; e += 2) {
;                 const f32x2_t r0 = {relu1(c0[4 * q + e]), relu1(c0[4 * q + e + 1])};
;                 const f32x2_t r1 = {relu1(c1[4 * q + e]), relu1(c1[4 * q + e + 1])};
;                 const f32x2_t w0 = {wv[0][q][e], wv[0][q][e + 1]}, w1 = {wv[1][q][e], wv[1][q][e + 1]};
;                 a0 = __builtin_elementwise_fma(r0, w0, a0); a1 = __builtin_elementwise_fma(r1, w1, a1); }
;         float s0 = a0.x + a0.y, s1 = a1.x + a1.y;
;         s0 += __shfl_xor(s0, 32); s1 += __shfl_xor(s1, 32);
;         if (h2 == 0) { sc0[kt * 64 + 32 * sub + r32] = s0; sc1[kt * 64 + 32 * sub + r32] = s1; }
.LBB0_1880:
	ds_read_b128 v[0:3], v207 offset:17408
	ds_read_b128 v[210:213], v207 offset:17440
	ds_read_b128 v[214:217], v207 offset:17472
	ds_read_b128 v[218:221], v207 offset:17504
	ds_read_b128 v[222:225], v207 offset:17536
	ds_read_b128 v[226:229], v207 offset:17568
	ds_read_b128 v[230:233], v207 offset:17600
	ds_read_b128 v[234:237], v207 offset:17632
	ds_read_b128 v[176:179], v207 offset:26112
	ds_read_b128 v[172:175], v207 offset:26144
	ds_read_b128 v[168:171], v207 offset:26176
	ds_read_b128 v[164:167], v207 offset:26208
	ds_read_b128 v[160:163], v207 offset:26240
	ds_read_b128 v[156:159], v207 offset:26272
	ds_read_b128 v[152:155], v207 offset:26304
	ds_read_b128 v[148:151], v207 offset:26336
	s_waitcnt lgkmcnt(15)
	v_mfma_f32_32x32x16_f16 v[16:31], v[36:39], v[0:3], 0
	s_waitcnt lgkmcnt(14)
	v_mfma_f32_32x32x16_f16 v[16:31], v[40:43], v[210:213], v[16:31]
	s_waitcnt lgkmcnt(13)
	v_mfma_f32_32x32x16_f16 v[16:31], v[44:47], v[214:217], v[16:31]
	s_waitcnt lgkmcnt(12)
	v_mfma_f32_32x32x16_f16 v[16:31], v[48:51], v[218:221], v[16:31]
	s_waitcnt lgkmcnt(11)
	v_mfma_f32_32x32x16_f16 v[16:31], v[52:55], v[222:225], v[16:31]
	s_waitcnt lgkmcnt(10)
	v_mfma_f32_32x32x16_f16 v[16:31], v[56:59], v[226:229], v[16:31]
	s_waitcnt lgkmcnt(9)
	v_mfma_f32_32x32x16_f16 v[16:31], v[60:63], v[230:233], v[16:31]
	s_waitcnt lgkmcnt(8)
	v_mfma_f32_32x32x16_f16 v[16:31], v[64:67], v[234:237], v[16:31]
	v_mfma_f32_32x32x16_f16 v[0:15], v[84:87], v[0:3], 0
	v_mfma_f32_32x32x16_f16 v[0:15], v[88:91], v[210:213], v[0:15]
	v_mfma_f32_32x32x16_f16 v[0:15], v[92:95], v[214:217], v[0:15]
	s_nop 8
	v_max_i32_e32 v16, 0, v16
	v_max_i32_e32 v17, 0, v17
	v_fma_f32 v238, v16, v68, 0
	v_fma_f32 v239, v17, v69, 0
	v_max_i32_e32 v18, 0, v18
	v_max_i32_e32 v19, 0, v19
	v_fma_f32 v238, v18, v70, v238
	v_mfma_f32_32x32x16_f16 v[0:15], v[96:99], v[218:221], v[0:15]
	v_fma_f32 v239, v19, v71, v239
	v_max_i32_e32 v20, 0, v20
	v_max_i32_e32 v21, 0, v21
	v_fma_f32 v238, v20, v72, v238
	v_fma_f32 v239, v21, v73, v239
	v_max_i32_e32 v22, 0, v22
	v_max_i32_e32 v23, 0, v23
	v_mfma_f32_32x32x16_f16 v[0:15], v[100:103], v[222:225], v[0:15]
	v_fma_f32 v238, v22, v74, v238
	v_fma_f32 v239, v23, v75, v239
	v_max_i32_e32 v24, 0, v24
	v_max_i32_e32 v25, 0, v25
	v_fma_f32 v238, v24, v76, v238
	v_fma_f32 v239, v25, v77, v239
	v_mfma_f32_32x32x16_f16 v[0:15], v[104:107], v[226:229], v[0:15]
	v_max_i32_e32 v26, 0, v26
	v_max_i32_e32 v27, 0, v27
	v_fma_f32 v238, v26, v78, v238
	v_fma_f32 v239, v27, v79, v239
	v_max_i32_e32 v28, 0, v28
	v_max_i32_e32 v29, 0, v29
	v_mfma_f32_32x32x16_f16 v[0:15], v[108:111], v[230:233], v[0:15]
	v_fma_f32 v238, v28, v80, v238
	v_fma_f32 v239, v29, v81, v239
	v_max_i32_e32 v30, 0, v30
	v_max_i32_e32 v31, 0, v31
	v_fma_f32 v238, v30, v82, v238
	v_fma_f32 v239, v31, v83, v239
	v_mfma_f32_32x32x16_f16 v[0:15], v[112:115], v[234:237], v[0:15]
	v_add_f32_e32 v240, v238, v239
	v_mov_b32_e32 v241, v240
	v_lshlrev_b32_e32 v242, 2, v32
	s_nop 0
	v_permlane32_swap_b32_e32 v241, v240
	v_add_f32_e32 v241, v241, v240
	s_mov_b64 exec, s[4:5]
	global_store_dword v242, v241, s[6:7] offset:256
	s_mov_b64 exec, -1
	s_waitcnt lgkmcnt(0)
; #define LAS __attribute__((address_space(3)))
; DI void indexer_tile(const LAS unsigned char* buf, const f16x8 (&af)[2][8], const f32x4 (&wv)[2][4], float* sc0, float* sc1, int kt, int r32, int h2) {
;     ...
;     for (int sub = 0; sub < 2; ++sub) {
;         f32x16 c0, c1;
; #pragma unroll
;         for (int i = 0; i < 16; ++i) { c0[i] = 0.f; c1[i] = 0.f; }
; #pragma unroll
;         for (int ks = 0; ks < 8; ++ks) { c0 = __builtin_amdgcn_mfma_f32_32x32x16_f16(af[0][ks], bfr[sub][ks], c0, 0, 0, 0); c1 = __builtin_amdgcn_mfma_f32_32x32x16_f16(af[1][ks], bfr[sub][ks], c1, 0, 0, 0); }
;         f32x2_t a0 = {0.f, 0.f}, a1 = {0.f, 0.f};
; #pragma unroll
;         for (int q = 0; q < 4; ++q)
; #pragma unroll
;             for (int e = 0; e < 4; e += 2) {
;                 const f32x2_t r0 = {relu1(c0[4 * q + e]), relu1(c0[4 * q + e + 1])};
;                 const f32x2_t r1 = {relu1(c1[4 * q + e]), relu1(c1[4 * q + e + 1])};
;                 const f32x2_t w0 = {wv[0][q][e], wv[0][q][e + 1]}, w1 = {wv[1][q][e], wv[1][q][e + 1]};
;                 a0 = __builtin_elementwise_fma(r0, w0, a0); a1 = __builtin_elementwise_fma(r1, w1, a1); }
;         float s0 = a0.x + a0.y, s1 = a1.x + a1.y;
;         s0 += __shfl_xor(s0, 32); s1 += __shfl_xor(s1, 32);
;         if (h2 == 0) { sc0[kt * 64 + 32 * sub + r32] = s0; sc1[kt * 64 + 32 * sub + r32] = s1; }
; DI void indexer_phase(const unsigned short* QI, const unsigned short* KI16, const float* WI, float* SC, LAS unsigned char* lds, int tid, int bid, int G) {
;     ...
;                 if (kt + 2 < nt) { *(LAS u32x4*)(buf0 + key0 * KT_ROWB + ch * 16) = a0; *(LAS u32x4*)(buf0 + (key0 + 32) * KT_ROWB + ch * 16) = a1; }
	v_mfma_f32_32x32x16_f16 v[16:31], v[36:39], v[176:179], 0
	v_mfma_f32_32x32x16_f16 v[16:31], v[40:43], v[172:175], v[16:31]
	v_mfma_f32_32x32x16_f16 v[16:31], v[44:47], v[168:171], v[16:31]
	s_nop 8
	v_max_i32_e32 v0, 0, v0
	v_max_i32_e32 v1, 0, v1
	v_fma_f32 v243, v0, v116, 0
	v_fma_f32 v244, v1, v117, 0
	v_max_i32_e32 v2, 0, v2
	v_max_i32_e32 v3, 0, v3
	v_fma_f32 v243, v2, v118, v243
	v_mfma_f32_32x32x16_f16 v[16:31], v[48:51], v[164:167], v[16:31]
	v_fma_f32 v244, v3, v119, v244
	v_max_i32_e32 v4, 0, v4
	v_max_i32_e32 v5, 0, v5
	v_fma_f32 v243, v4, v120, v243
	v_fma_f32 v244, v5, v121, v244
	v_max_i32_e32 v6, 0, v6
	v_max_i32_e32 v7, 0, v7
	v_mfma_f32_32x32x16_f16 v[16:31], v[52:55], v[160:163], v[16:31]
	v_fma_f32 v243, v6, v122, v243
	v_fma_f32 v244, v7, v123, v244
	v_max_i32_e32 v8, 0, v8
	v_max_i32_e32 v9, 0, v9
	v_fma_f32 v243, v8, v124, v243
	v_fma_f32 v244, v9, v125, v244
	v_mfma_f32_32x32x16_f16 v[16:31], v[56:59], v[156:159], v[16:31]
	v_max_i32_e32 v10, 0, v10
	v_max_i32_e32 v11, 0, v11
	v_fma_f32 v243, v10, v126, v243
	v_fma_f32 v244, v11, v127, v244
	v_max_i32_e32 v12, 0, v12
	v_max_i32_e32 v13, 0, v13
	v_mfma_f32_32x32x16_f16 v[16:31], v[60:63], v[152:155], v[16:31]
	v_fma_f32 v243, v12, v128, v243
	v_fma_f32 v244, v13, v129, v244
	v_max_i32_e32 v14, 0, v14
	v_max_i32_e32 v15, 0, v15
	v_fma_f32 v243, v14, v130, v243
	v_fma_f32 v244, v15, v131, v244
	v_mfma_f32_32x32x16_f16 v[16:31], v[64:67], v[148:151], v[16:31]
	v_add_f32_e32 v245, v243, v244
	v_mov_b32_e32 v246, v245
	v_lshlrev_b32_e32 v247, 2, v32
	s_nop 0
	v_permlane32_swap_b32_e32 v246, v245
	v_add_f32_e32 v246, v246, v245
	s_mov_b64 exec, s[4:5]
	global_store_dword v247, v246, s[8:9] offset:256
	s_mov_b64 exec, -1
	v_mfma_f32_32x32x16_f16 v[0:15], v[84:87], v[176:179], 0
	v_mfma_f32_32x32x16_f16 v[0:15], v[88:91], v[172:175], v[0:15]
	v_mfma_f32_32x32x16_f16 v[0:15], v[92:95], v[168:171], v[0:15]
	s_nop 8
	v_max_i32_e32 v16, 0, v16
	v_max_i32_e32 v17, 0, v17
	v_fma_f32 v238, v16, v68, 0
	v_fma_f32 v239, v17, v69, 0
	v_max_i32_e32 v18, 0, v18
	v_max_i32_e32 v19, 0, v19
	v_fma_f32 v238, v18, v70, v238
	v_mfma_f32_32x32x16_f16 v[0:15], v[96:99], v[164:167], v[0:15]
	v_fma_f32 v239, v19, v71, v239
	v_max_i32_e32 v20, 0, v20
	v_max_i32_e32 v21, 0, v21
	v_fma_f32 v238, v20, v72, v238
	v_fma_f32 v239, v21, v73, v239
	v_max_i32_e32 v22, 0, v22
	v_max_i32_e32 v23, 0, v23
	v_mfma_f32_32x32x16_f16 v[0:15], v[100:103], v[160:163], v[0:15]
	v_fma_f32 v238, v22, v74, v238
	v_fma_f32 v239, v23, v75, v239
	v_max_i32_e32 v24, 0, v24
	v_max_i32_e32 v25, 0, v25
	v_fma_f32 v238, v24, v76, v238
	v_fma_f32 v239, v25, v77, v239
	v_mfma_f32_32x32x16_f16 v[0:15], v[104:107], v[156:159], v[0:15]
	v_max_i32_e32 v26, 0, v26
	v_max_i32_e32 v27, 0, v27
	v_fma_f32 v238, v26, v78, v238
	v_fma_f32 v239, v27, v79, v239
	v_max_i32_e32 v28, 0, v28
	v_max_i32_e32 v29, 0, v29
	v_mfma_f32_32x32x16_f16 v[0:15], v[108:111], v[152:155], v[0:15]
	v_fma_f32 v238, v28, v80, v238
	v_fma_f32 v239, v29, v81, v239
	v_max_i32_e32 v30, 0, v30
	v_max_i32_e32 v31, 0, v31
	v_fma_f32 v238, v30, v82, v238
	v_fma_f32 v239, v31, v83, v239
	v_mfma_f32_32x32x16_f16 v[0:15], v[112:115], v[148:151], v[0:15]
	v_add_f32_e32 v240, v238, v239
	v_mov_b32_e32 v241, v240
	v_lshlrev_b32_e32 v242, 2, v32
	s_nop 0
	v_permlane32_swap_b32_e32 v241, v240
	v_add_f32_e32 v241, v241, v240
	s_mov_b64 exec, s[4:5]
	global_store_dword v242, v241, s[6:7] offset:384
	s_mov_b64 exec, -1
	s_nop 11
	v_max_i32_e32 v0, 0, v0
	v_max_i32_e32 v1, 0, v1
	v_fma_f32 v243, v0, v116, 0
	v_fma_f32 v244, v1, v117, 0
	v_max_i32_e32 v2, 0, v2
	v_max_i32_e32 v3, 0, v3
	v_fma_f32 v243, v2, v118, v243
	v_fma_f32 v244, v3, v119, v244
	v_max_i32_e32 v4, 0, v4
	v_max_i32_e32 v5, 0, v5
	v_fma_f32 v243, v4, v120, v243
	v_fma_f32 v244, v5, v121, v244
	v_max_i32_e32 v6, 0, v6
	v_max_i32_e32 v7, 0, v7
	v_fma_f32 v243, v6, v122, v243
	v_fma_f32 v244, v7, v123, v244
	v_max_i32_e32 v8, 0, v8
	v_max_i32_e32 v9, 0, v9
	v_fma_f32 v243, v8, v124, v243
	v_fma_f32 v244, v9, v125, v244
	v_max_i32_e32 v10, 0, v10
	v_max_i32_e32 v11, 0, v11
	v_fma_f32 v243, v10, v126, v243
	v_fma_f32 v244, v11, v127, v244
	v_max_i32_e32 v12, 0, v12
	v_max_i32_e32 v13, 0, v13
	v_fma_f32 v243, v12, v128, v243
	v_fma_f32 v244, v13, v129, v244
	v_max_i32_e32 v14, 0, v14
	v_max_i32_e32 v15, 0, v15
	v_fma_f32 v243, v14, v130, v243
	v_fma_f32 v244, v15, v131, v244
	v_add_f32_e32 v245, v243, v244
	v_mov_b32_e32 v246, v245
	v_lshlrev_b32_e32 v247, 2, v32
	s_nop 0
	v_permlane32_swap_b32_e32 v246, v245
	v_add_f32_e32 v246, v246, v245
	s_mov_b64 exec, s[4:5]
	global_store_dword v247, v246, s[8:9] offset:384
	s_mov_b64 exec, -1
	s_andn2_b64 vcc, exec, s[10:11]
	s_cbranch_vccnz .LBB0_1868
	s_waitcnt vmcnt(8)
	ds_write_b128 v209, v[132:135]
	ds_write_b128 v209, v[136:139] offset:8704
	s_branch .LBB0_1868

; #define LAS __attribute__((address_space(3)))
; DI size_t sc_row_off(int b, int s) { const int qb = s >> 7; return ((size_t)(b * 2080 + ((qb * (qb + 1)) >> 1))) * 16384 + (size_t)(s & 127) * ((qb + 1) * 128); }
; DI void indexer_phase(const unsigned short* QI, const unsigned short* KI16, const float* WI, float* SC, LAS unsigned char* lds, int tid, int bid, int G) {
;     ...
;         for (int it = 0; it < 4; ++it) {
;             const int b = it >> 1, gi = (it & 1) ? (511 - v) : v; const int tb = 16 * gi;
;             const int nt = ((tb + 15) >> 6) + 1;
;             f16x8 af[2][8]; f32x4 wv[2][4];
; #pragma unroll
;             for (int tq = 0; tq < 2; ++tq) { const size_t tg = (size_t)b * SEQ + tb + 2 * w + tq;
; #pragma unroll
;                 for (int ks = 0; ks < 8; ++ks) af[tq][ks] = *(const f16x8*)(QI + tg * 4096 + r32 * 128 + 16 * ks + 8 * h2);
; #pragma unroll
;                 for (int q = 0; q < 4; ++q) wv[tq][q] = *(const f32x4*)(WI + tg * 32 + 8 * q + 4 * h2); }
;             float* sc0 = SC + sc_row_off(b, tb + 2 * w); float* sc1 = SC + sc_row_off(b, tb + 2 * w + 1);
;             const unsigned short* src = KI16 + (size_t)b * SEQ * 128 + (size_t)key0 * 128 + ch * 8;
;             u32x4 a0, a1, b0 = {0u, 0u, 0u, 0u}, b1 = {0u, 0u, 0u, 0u};
;             a0 = *(const u32x4*)src; a1 = *(const u32x4*)(src + 32 * 128);
;             if (nt > 1) { b0 = *(const u32x4*)(src + 64 * 128); b1 = *(const u32x4*)(src + 96 * 128); }
;             __syncthreads();
;             *(LAS u32x4*)(buf0 + key0 * KT_ROWB + ch * 16) = a0; *(LAS u32x4*)(buf0 + (key0 + 32) * KT_ROWB + ch * 16) = a1;
;             __syncthreads();
.LBB0_1887:
	s_add_u32 s6, s38, s45
	s_addc_u32 s7, s39, 0
	s_lshl_b64 s[8:9], s[6:7], 13
	v_lshl_add_u64 v[0:1], v[180:181], 0, s[8:9]
	s_lshl_b64 s[8:9], s[6:7], 7
	s_or_b32 s6, s6, 1
	global_load_dwordx4 v[34:37], v[0:1], off
	global_load_dwordx4 v[38:41], v[0:1], off offset:32
	global_load_dwordx4 v[42:45], v[0:1], off offset:64
	global_load_dwordx4 v[46:49], v[0:1], off offset:96
	global_load_dwordx4 v[50:53], v[0:1], off offset:128
	global_load_dwordx4 v[54:57], v[0:1], off offset:160
	global_load_dwordx4 v[58:61], v[0:1], off offset:192
	global_load_dwordx4 v[62:65], v[0:1], off offset:224
	v_lshl_add_u64 v[0:1], v[182:183], 0, s[8:9]
	s_lshl_b64 s[8:9], s[6:7], 13
	global_load_dwordx4 v[66:69], v[0:1], off
	global_load_dwordx4 v[70:73], v[0:1], off offset:32
	global_load_dwordx4 v[74:77], v[0:1], off offset:64
	global_load_dwordx4 v[78:81], v[0:1], off offset:96
	v_lshl_add_u64 v[0:1], v[180:181], 0, s[8:9]
	global_load_dwordx4 v[82:85], v[0:1], off
	global_load_dwordx4 v[86:89], v[0:1], off offset:32
	global_load_dwordx4 v[90:93], v[0:1], off offset:64
	global_load_dwordx4 v[94:97], v[0:1], off offset:96
	global_load_dwordx4 v[98:101], v[0:1], off offset:128
	global_load_dwordx4 v[102:105], v[0:1], off offset:160
	global_load_dwordx4 v[106:109], v[0:1], off offset:192
	global_load_dwordx4 v[110:113], v[0:1], off offset:224
	s_lshl_b64 s[6:7], s[6:7], 7
	v_lshl_add_u64 v[0:1], v[182:183], 0, s[6:7]
	global_load_dwordx4 v[130:133], v[192:193], off
	global_load_dwordx4 v[138:141], v[194:195], off
	global_load_dwordx4 v[114:117], v[0:1], off
	global_load_dwordx4 v[118:121], v[0:1], off offset:32
	global_load_dwordx4 v[134:137], v[198:199], off
	global_load_dwordx4 v[142:145], v[196:197], off
	global_load_dwordx4 v[122:125], v[0:1], off offset:64
	global_load_dwordx4 v[126:129], v[0:1], off offset:96
	s_lshl_b64 s[6:7], s[18:19], 16
	s_add_u32 s6, s17, s6
	s_addc_u32 s7, s33, s7
	s_add_u32 s8, s6, 0x8200000
	s_addc_u32 s9, s7, 0
	s_add_u32 s6, s8, s20
	s_addc_u32 s7, s9, s21
	s_add_u32 s8, s8, s22
	s_addc_u32 s9, s9, s23
	s_mov_b32 s14, 3
	v_mov_b32_e32 v32, v206
	v_mov_b64_e32 v[178:179], v[202:203]
	s_barrier
	s_waitcnt vmcnt(7)
	ds_write_b128 v209, v[130:133]
	s_waitcnt vmcnt(0)
	ds_write_b128 v209, v[138:141] offset:8704
	s_waitcnt lgkmcnt(0)
	s_barrier
	s_branch .LBB0_1889

; #define LAS __attribute__((address_space(3)))
; DI void indexer_tile(const LAS unsigned char* buf, const f16x8 (&af)[2][8], const f32x4 (&wv)[2][4], float* sc0, float* sc1, int kt, int r32, int h2) {
;     ...
;         for (int ks = 0; ks < 8; ++ks) bfr[sub][ks] = *(const LAS f16x8*)(buf + (32 * sub + r32) * KT_ROWB + (16 * ks + 8 * h2) * 2);
;     __builtin_amdgcn_sched_barrier(0);
; #pragma unroll
;     for (int sub = 0; sub < 2; ++sub) {
;         f32x16 c0, c1;
; #pragma unroll
;         for (int i = 0; i < 16; ++i) { c0[i] = 0.f; c1[i] = 0.f; }
; #pragma unroll
;         for (int ks = 0; ks < 8; ++ks) { c0 = __builtin_amdgcn_mfma_f32_32x32x16_f16(af[0][ks], bfr[sub][ks], c0, 0, 0, 0); c1 = __builtin_amdgcn_mfma_f32_32x32x16_f16(af[1][ks], bfr[sub][ks], c1, 0, 0, 0); }
;         f32x2_t a0 = {0.f, 0.f}, a1 = {0.f, 0.f};
; #pragma unroll
;         for (int q = 0; q < 4; ++q)
; #pragma unroll
;             for (int e = 0; e < 4; e += 2) {
;                 const f32x2_t r0 = {relu1(c0[4 * q + e]), relu1(c0[4 * q + e + 1])};
;                 const f32x2_t r1 = {relu1(c1[4 * q + e]), relu1(c1[4 * q + e + 1])};
;                 const f32x2_t w0 = {wv[0][q][e], wv[0][q][e + 1]}, w1 = {wv[1][q][e], wv[1][q][e + 1]};
;                 a0 = __builtin_elementwise_fma(r0, w0, a0); a1 = __builtin_elementwise_fma(r1, w1, a1); }
;         float s0 = a0.x + a0.y, s1 = a1.x + a1.y;
;         s0 += __shfl_xor(s0, 32); s1 += __shfl_xor(s1, 32);
;         if (h2 == 0) { sc0[kt * 64 + 32 * sub + r32] = s0; sc1[kt * 64 + 32 * sub + r32] = s1; }
.LBB0_1891:
	ds_read_b128 v[0:3], v207
	ds_read_b128 v[210:213], v207 offset:32
	ds_read_b128 v[214:217], v207 offset:64
	ds_read_b128 v[218:221], v207 offset:96
	ds_read_b128 v[222:225], v207 offset:128
	ds_read_b128 v[226:229], v207 offset:160
	ds_read_b128 v[230:233], v207 offset:192
	ds_read_b128 v[234:237], v207 offset:224
	ds_read_b128 v[174:177], v207 offset:8704
	ds_read_b128 v[170:173], v207 offset:8736
	ds_read_b128 v[166:169], v207 offset:8768
	ds_read_b128 v[162:165], v207 offset:8800
	ds_read_b128 v[158:161], v207 offset:8832
	ds_read_b128 v[154:157], v207 offset:8864
	ds_read_b128 v[150:153], v207 offset:8896
	ds_read_b128 v[146:149], v207 offset:8928
	s_waitcnt lgkmcnt(15)
	v_mfma_f32_32x32x16_f16 v[16:31], v[34:37], v[0:3], 0
	s_waitcnt lgkmcnt(14)
	v_mfma_f32_32x32x16_f16 v[16:31], v[38:41], v[210:213], v[16:31]
	s_waitcnt lgkmcnt(13)
	v_mfma_f32_32x32x16_f16 v[16:31], v[42:45], v[214:217], v[16:31]
	s_waitcnt lgkmcnt(12)
	v_mfma_f32_32x32x16_f16 v[16:31], v[46:49], v[218:221], v[16:31]
	s_waitcnt lgkmcnt(11)
	v_mfma_f32_32x32x16_f16 v[16:31], v[50:53], v[222:225], v[16:31]
	s_waitcnt lgkmcnt(10)
	v_mfma_f32_32x32x16_f16 v[16:31], v[54:57], v[226:229], v[16:31]
	s_waitcnt lgkmcnt(9)
	v_mfma_f32_32x32x16_f16 v[16:31], v[58:61], v[230:233], v[16:31]
	s_waitcnt lgkmcnt(8)
	v_mfma_f32_32x32x16_f16 v[16:31], v[62:65], v[234:237], v[16:31]
	v_mfma_f32_32x32x16_f16 v[0:15], v[82:85], v[0:3], 0
	v_mfma_f32_32x32x16_f16 v[0:15], v[86:89], v[210:213], v[0:15]
	v_mfma_f32_32x32x16_f16 v[0:15], v[90:93], v[214:217], v[0:15]
	s_nop 8
	v_max_i32_e32 v16, 0, v16
	v_max_i32_e32 v17, 0, v17
	v_fma_f32 v238, v16, v66, 0
	v_fma_f32 v239, v17, v67, 0
	v_max_i32_e32 v18, 0, v18
	v_max_i32_e32 v19, 0, v19
	v_fma_f32 v238, v18, v68, v238
	v_mfma_f32_32x32x16_f16 v[0:15], v[94:97], v[218:221], v[0:15]
	v_fma_f32 v239, v19, v69, v239
	v_max_i32_e32 v20, 0, v20
	v_max_i32_e32 v21, 0, v21
	v_fma_f32 v238, v20, v70, v238
	v_fma_f32 v239, v21, v71, v239
	v_max_i32_e32 v22, 0, v22
	v_max_i32_e32 v23, 0, v23
	v_mfma_f32_32x32x16_f16 v[0:15], v[98:101], v[222:225], v[0:15]
	v_fma_f32 v238, v22, v72, v238
	v_fma_f32 v239, v23, v73, v239
	v_max_i32_e32 v24, 0, v24
	v_max_i32_e32 v25, 0, v25
	v_fma_f32 v238, v24, v74, v238
	v_fma_f32 v239, v25, v75, v239
	v_mfma_f32_32x32x16_f16 v[0:15], v[102:105], v[226:229], v[0:15]
	v_max_i32_e32 v26, 0, v26
	v_max_i32_e32 v27, 0, v27
	v_fma_f32 v238, v26, v76, v238
	v_fma_f32 v239, v27, v77, v239
	v_max_i32_e32 v28, 0, v28
	v_max_i32_e32 v29, 0, v29
	v_mfma_f32_32x32x16_f16 v[0:15], v[106:109], v[230:233], v[0:15]
	v_fma_f32 v238, v28, v78, v238
	v_fma_f32 v239, v29, v79, v239
	v_max_i32_e32 v30, 0, v30
	v_max_i32_e32 v31, 0, v31
	v_fma_f32 v238, v30, v80, v238
	v_fma_f32 v239, v31, v81, v239
	v_mfma_f32_32x32x16_f16 v[0:15], v[110:113], v[234:237], v[0:15]
	v_add_f32_e32 v240, v238, v239
	v_mov_b32_e32 v241, v240
	v_lshlrev_b32_e32 v242, 2, v32
	s_nop 0
	v_permlane32_swap_b32_e32 v241, v240
	v_add_f32_e32 v241, v241, v240
	s_mov_b64 exec, s[4:5]
	global_store_dword v242, v241, s[6:7]
	s_mov_b64 exec, -1
	s_waitcnt lgkmcnt(0)
; #define LAS __attribute__((address_space(3)))
; DI void indexer_tile(const LAS unsigned char* buf, const f16x8 (&af)[2][8], const f32x4 (&wv)[2][4], float* sc0, float* sc1, int kt, int r32, int h2) {
;     ...
;     for (int sub = 0; sub < 2; ++sub) {
;         f32x16 c0, c1;
; #pragma unroll
;         for (int i = 0; i < 16; ++i) { c0[i] = 0.f; c1[i] = 0.f; }
; #pragma unroll
;         for (int ks = 0; ks < 8; ++ks) { c0 = __builtin_amdgcn_mfma_f32_32x32x16_f16(af[0][ks], bfr[sub][ks], c0, 0, 0, 0); c1 = __builtin_amdgcn_mfma_f32_32x32x16_f16(af[1][ks], bfr[sub][ks], c1, 0, 0, 0); }
;         f32x2_t a0 = {0.f, 0.f}, a1 = {0.f, 0.f};
; #pragma unroll
;         for (int q = 0; q < 4; ++q)
; #pragma unroll
;             for (int e = 0; e < 4; e += 2) {
;                 const f32x2_t r0 = {relu1(c0[4 * q + e]), relu1(c0[4 * q + e + 1])};
;                 const f32x2_t r1 = {relu1(c1[4 * q + e]), relu1(c1[4 * q + e + 1])};
;                 const f32x2_t w0 = {wv[0][q][e], wv[0][q][e + 1]}, w1 = {wv[1][q][e], wv[1][q][e + 1]};
;                 a0 = __builtin_elementwise_fma(r0, w0, a0); a1 = __builtin_elementwise_fma(r1, w1, a1); }
;         float s0 = a0.x + a0.y, s1 = a1.x + a1.y;
;         s0 += __shfl_xor(s0, 32); s1 += __shfl_xor(s1, 32);
;         if (h2 == 0) { sc0[kt * 64 + 32 * sub + r32] = s0; sc1[kt * 64 + 32 * sub + r32] = s1; }
; DI void indexer_phase(const unsigned short* QI, const unsigned short* KI16, const float* WI, float* SC, LAS unsigned char* lds, int tid, int bid, int G) {
;     ...
;                 if (kt + 1 < nt) { *(LAS u32x4*)(buf1 + key0 * KT_ROWB + ch * 16) = b0; *(LAS u32x4*)(buf1 + (key0 + 32) * KT_ROWB + ch * 16) = b1; }
	v_mfma_f32_32x32x16_f16 v[16:31], v[34:37], v[174:177], 0
	v_mfma_f32_32x32x16_f16 v[16:31], v[38:41], v[170:173], v[16:31]
	v_mfma_f32_32x32x16_f16 v[16:31], v[42:45], v[166:169], v[16:31]
	s_nop 8
	v_max_i32_e32 v0, 0, v0
	v_max_i32_e32 v1, 0, v1
	v_fma_f32 v243, v0, v114, 0
	v_fma_f32 v244, v1, v115, 0
	v_max_i32_e32 v2, 0, v2
	v_max_i32_e32 v3, 0, v3
	v_fma_f32 v243, v2, v116, v243
	v_mfma_f32_32x32x16_f16 v[16:31], v[46:49], v[162:165], v[16:31]
	v_fma_f32 v244, v3, v117, v244
	v_max_i32_e32 v4, 0, v4
	v_max_i32_e32 v5, 0, v5
	v_fma_f32 v243, v4, v118, v243
	v_fma_f32 v244, v5, v119, v244
	v_max_i32_e32 v6, 0, v6
	v_max_i32_e32 v7, 0, v7
	v_mfma_f32_32x32x16_f16 v[16:31], v[50:53], v[158:161], v[16:31]
	v_fma_f32 v243, v6, v120, v243
	v_fma_f32 v244, v7, v121, v244
	v_max_i32_e32 v8, 0, v8
	v_max_i32_e32 v9, 0, v9
	v_fma_f32 v243, v8, v122, v243
	v_fma_f32 v244, v9, v123, v244
	v_mfma_f32_32x32x16_f16 v[16:31], v[54:57], v[154:157], v[16:31]
	v_max_i32_e32 v10, 0, v10
	v_max_i32_e32 v11, 0, v11
	v_fma_f32 v243, v10, v124, v243
	v_fma_f32 v244, v11, v125, v244
	v_max_i32_e32 v12, 0, v12
	v_max_i32_e32 v13, 0, v13
	v_mfma_f32_32x32x16_f16 v[16:31], v[58:61], v[150:153], v[16:31]
	v_fma_f32 v243, v12, v126, v243
	v_fma_f32 v244, v13, v127, v244
	v_max_i32_e32 v14, 0, v14
	v_max_i32_e32 v15, 0, v15
	v_fma_f32 v243, v14, v128, v243
	v_fma_f32 v244, v15, v129, v244
	v_mfma_f32_32x32x16_f16 v[16:31], v[62:65], v[146:149], v[16:31]
	v_add_f32_e32 v245, v243, v244
	v_mov_b32_e32 v246, v245
	v_lshlrev_b32_e32 v247, 2, v32
	s_nop 0
	v_permlane32_swap_b32_e32 v246, v245
	v_add_f32_e32 v246, v246, v245
	s_mov_b64 exec, s[4:5]
	global_store_dword v247, v246, s[8:9]
	s_mov_b64 exec, -1
	v_mfma_f32_32x32x16_f16 v[0:15], v[82:85], v[174:177], 0
	v_mfma_f32_32x32x16_f16 v[0:15], v[86:89], v[170:173], v[0:15]
	v_mfma_f32_32x32x16_f16 v[0:15], v[90:93], v[166:169], v[0:15]
	s_nop 8
	v_max_i32_e32 v16, 0, v16
	v_max_i32_e32 v17, 0, v17
	v_fma_f32 v238, v16, v66, 0
	v_fma_f32 v239, v17, v67, 0
	v_max_i32_e32 v18, 0, v18
	v_max_i32_e32 v19, 0, v19
	v_fma_f32 v238, v18, v68, v238
	v_mfma_f32_32x32x16_f16 v[0:15], v[94:97], v[162:165], v[0:15]
	v_fma_f32 v239, v19, v69, v239
	v_max_i32_e32 v20, 0, v20
	v_max_i32_e32 v21, 0, v21
	v_fma_f32 v238, v20, v70, v238
	v_fma_f32 v239, v21, v71, v239
	v_max_i32_e32 v22, 0, v22
	v_max_i32_e32 v23, 0, v23
	v_mfma_f32_32x32x16_f16 v[0:15], v[98:101], v[158:161], v[0:15]
	v_fma_f32 v238, v22, v72, v238
	v_fma_f32 v239, v23, v73, v239
	v_max_i32_e32 v24, 0, v24
	v_max_i32_e32 v25, 0, v25
	v_fma_f32 v238, v24, v74, v238
	v_fma_f32 v239, v25, v75, v239
	v_mfma_f32_32x32x16_f16 v[0:15], v[102:105], v[154:157], v[0:15]
	v_max_i32_e32 v26, 0, v26
	v_max_i32_e32 v27, 0, v27
	v_fma_f32 v238, v26, v76, v238
	v_fma_f32 v239, v27, v77, v239
	v_max_i32_e32 v28, 0, v28
	v_max_i32_e32 v29, 0, v29
	v_mfma_f32_32x32x16_f16 v[0:15], v[106:109], v[150:153], v[0:15]
	v_fma_f32 v238, v28, v78, v238
	v_fma_f32 v239, v29, v79, v239
	v_max_i32_e32 v30, 0, v30
	v_max_i32_e32 v31, 0, v31
	v_fma_f32 v238, v30, v80, v238
	v_fma_f32 v239, v31, v81, v239
	v_mfma_f32_32x32x16_f16 v[0:15], v[110:113], v[146:149], v[0:15]
	v_add_f32_e32 v240, v238, v239
	v_mov_b32_e32 v241, v240
	v_lshlrev_b32_e32 v242, 2, v32
	s_nop 0
	v_permlane32_swap_b32_e32 v241, v240
	v_add_f32_e32 v241, v241, v240
	s_mov_b64 exec, s[4:5]
	global_store_dword v242, v241, s[6:7] offset:128
	s_mov_b64 exec, -1
	s_nop 11
	v_max_i32_e32 v0, 0, v0
	v_max_i32_e32 v1, 0, v1
	v_fma_f32 v243, v0, v114, 0
	v_fma_f32 v244, v1, v115, 0
	v_max_i32_e32 v2, 0, v2
	v_max_i32_e32 v3, 0, v3
	v_fma_f32 v243, v2, v116, v243
	v_fma_f32 v244, v3, v117, v244
	v_max_i32_e32 v4, 0, v4
	v_max_i32_e32 v5, 0, v5
	v_fma_f32 v243, v4, v118, v243
	v_fma_f32 v244, v5, v119, v244
	v_max_i32_e32 v6, 0, v6
	v_max_i32_e32 v7, 0, v7
	v_fma_f32 v243, v6, v120, v243
	v_fma_f32 v244, v7, v121, v244
	v_max_i32_e32 v8, 0, v8
	v_max_i32_e32 v9, 0, v9
	v_fma_f32 v243, v8, v122, v243
	v_fma_f32 v244, v9, v123, v244
	v_max_i32_e32 v10, 0, v10
	v_max_i32_e32 v11, 0, v11
	v_fma_f32 v243, v10, v124, v243
	v_fma_f32 v244, v11, v125, v244
	v_max_i32_e32 v12, 0, v12
	v_max_i32_e32 v13, 0, v13
	v_fma_f32 v243, v12, v126, v243
	v_fma_f32 v244, v13, v127, v244
	v_max_i32_e32 v14, 0, v14
	v_max_i32_e32 v15, 0, v15
	v_fma_f32 v243, v14, v128, v243
	v_fma_f32 v244, v15, v129, v244
	v_add_f32_e32 v245, v243, v244
	v_mov_b32_e32 v246, v245
	v_lshlrev_b32_e32 v247, 2, v32
	s_nop 0
	v_permlane32_swap_b32_e32 v246, v245
	v_add_f32_e32 v246, v246, v245
	s_mov_b64 exec, s[4:5]
	global_store_dword v247, v246, s[8:9] offset:128
	s_mov_b64 exec, -1
	s_add_i32 s18, s14, -3
	s_cmp_lt_u32 s18, s42
	s_cselect_b64 s[12:13], -1, 0
	s_cmp_ge_u32 s18, s42
	s_cbranch_scc1 .LBB0_1897
	s_waitcnt vmcnt(8)
	ds_write_b128 v209, v[134:137] offset:17408
	ds_write_b128 v209, v[142:145] offset:26112

; #define LAS __attribute__((address_space(3)))
; DI void indexer_tile(const LAS unsigned char* buf, const f16x8 (&af)[2][8], const f32x4 (&wv)[2][4], float* sc0, float* sc1, int kt, int r32, int h2) {
;     ...
;         for (int ks = 0; ks < 8; ++ks) bfr[sub][ks] = *(const LAS f16x8*)(buf + (32 * sub + r32) * KT_ROWB + (16 * ks + 8 * h2) * 2);
;     __builtin_amdgcn_sched_barrier(0);
; #pragma unroll
;     for (int sub = 0; sub < 2; ++sub) {
;         f32x16 c0, c1;
; #pragma unroll
;         for (int i = 0; i < 16; ++i) { c0[i] = 0.f; c1[i] = 0.f; }
; #pragma unroll
;         for (int ks = 0; ks < 8; ++ks) { c0 = __builtin_amdgcn_mfma_f32_32x32x16_f16(af[0][ks], bfr[sub][ks], c0, 0, 0, 0); c1 = __builtin_amdgcn_mfma_f32_32x32x16_f16(af[1][ks], bfr[sub][ks], c1, 0, 0, 0); }
;         f32x2_t a0 = {0.f, 0.f}, a1 = {0.f, 0.f};
; #pragma unroll
;         for (int q = 0; q < 4; ++q)
; #pragma unroll
;             for (int e = 0; e < 4; e += 2) {
;                 const f32x2_t r0 = {relu1(c0[4 * q + e]), relu1(c0[4 * q + e + 1])};
;                 const f32x2_t r1 = {relu1(c1[4 * q + e]), relu1(c1[4 * q + e + 1])};
;                 const f32x2_t w0 = {wv[0][q][e], wv[0][q][e + 1]}, w1 = {wv[1][q][e], wv[1][q][e + 1]};
;                 a0 = __builtin_elementwise_fma(r0, w0, a0); a1 = __builtin_elementwise_fma(r1, w1, a1); }
;         float s0 = a0.x + a0.y, s1 = a1.x + a1.y;
;         s0 += __shfl_xor(s0, 32); s1 += __shfl_xor(s1, 32);
;         if (h2 == 0) { sc0[kt * 64 + 32 * sub + r32] = s0; sc1[kt * 64 + 32 * sub + r32] = s1; }
.LBB0_1900:
	ds_read_b128 v[0:3], v207 offset:17408
	ds_read_b128 v[210:213], v207 offset:17440
	ds_read_b128 v[214:217], v207 offset:17472
	ds_read_b128 v[218:221], v207 offset:17504
	ds_read_b128 v[222:225], v207 offset:17536
	ds_read_b128 v[226:229], v207 offset:17568
	ds_read_b128 v[230:233], v207 offset:17600
	ds_read_b128 v[234:237], v207 offset:17632
	ds_read_b128 v[174:177], v207 offset:26112
	ds_read_b128 v[170:173], v207 offset:26144
	ds_read_b128 v[166:169], v207 offset:26176
	ds_read_b128 v[162:165], v207 offset:26208
	ds_read_b128 v[158:161], v207 offset:26240
	ds_read_b128 v[154:157], v207 offset:26272
	ds_read_b128 v[150:153], v207 offset:26304
	ds_read_b128 v[146:149], v207 offset:26336
	s_waitcnt lgkmcnt(15)
	v_mfma_f32_32x32x16_f16 v[16:31], v[34:37], v[0:3], 0
	s_waitcnt lgkmcnt(14)
	v_mfma_f32_32x32x16_f16 v[16:31], v[38:41], v[210:213], v[16:31]
	s_waitcnt lgkmcnt(13)
	v_mfma_f32_32x32x16_f16 v[16:31], v[42:45], v[214:217], v[16:31]
	s_waitcnt lgkmcnt(12)
	v_mfma_f32_32x32x16_f16 v[16:31], v[46:49], v[218:221], v[16:31]
	s_waitcnt lgkmcnt(11)
	v_mfma_f32_32x32x16_f16 v[16:31], v[50:53], v[222:225], v[16:31]
	s_waitcnt lgkmcnt(10)
	v_mfma_f32_32x32x16_f16 v[16:31], v[54:57], v[226:229], v[16:31]
	s_waitcnt lgkmcnt(9)
	v_mfma_f32_32x32x16_f16 v[16:31], v[58:61], v[230:233], v[16:31]
	s_waitcnt lgkmcnt(8)
	v_mfma_f32_32x32x16_f16 v[16:31], v[62:65], v[234:237], v[16:31]
	v_mfma_f32_32x32x16_f16 v[0:15], v[82:85], v[0:3], 0
	v_mfma_f32_32x32x16_f16 v[0:15], v[86:89], v[210:213], v[0:15]
	v_mfma_f32_32x32x16_f16 v[0:15], v[90:93], v[214:217], v[0:15]
	s_nop 8
	v_max_i32_e32 v16, 0, v16
	v_max_i32_e32 v17, 0, v17
	v_fma_f32 v238, v16, v66, 0
	v_fma_f32 v239, v17, v67, 0
	v_max_i32_e32 v18, 0, v18
	v_max_i32_e32 v19, 0, v19
	v_fma_f32 v238, v18, v68, v238
	v_mfma_f32_32x32x16_f16 v[0:15], v[94:97], v[218:221], v[0:15]
	v_fma_f32 v239, v19, v69, v239
	v_max_i32_e32 v20, 0, v20
	v_max_i32_e32 v21, 0, v21
	v_fma_f32 v238, v20, v70, v238
	v_fma_f32 v239, v21, v71, v239
	v_max_i32_e32 v22, 0, v22
	v_max_i32_e32 v23, 0, v23
	v_mfma_f32_32x32x16_f16 v[0:15], v[98:101], v[222:225], v[0:15]
	v_fma_f32 v238, v22, v72, v238
	v_fma_f32 v239, v23, v73, v239
	v_max_i32_e32 v24, 0, v24
	v_max_i32_e32 v25, 0, v25
	v_fma_f32 v238, v24, v74, v238
	v_fma_f32 v239, v25, v75, v239
	v_mfma_f32_32x32x16_f16 v[0:15], v[102:105], v[226:229], v[0:15]
	v_max_i32_e32 v26, 0, v26
	v_max_i32_e32 v27, 0, v27
	v_fma_f32 v238, v26, v76, v238
	v_fma_f32 v239, v27, v77, v239
	v_max_i32_e32 v28, 0, v28
	v_max_i32_e32 v29, 0, v29
	v_mfma_f32_32x32x16_f16 v[0:15], v[106:109], v[230:233], v[0:15]
	v_fma_f32 v238, v28, v78, v238
	v_fma_f32 v239, v29, v79, v239
	v_max_i32_e32 v30, 0, v30
	v_max_i32_e32 v31, 0, v31
	v_fma_f32 v238, v30, v80, v238
	v_fma_f32 v239, v31, v81, v239
	v_mfma_f32_32x32x16_f16 v[0:15], v[110:113], v[234:237], v[0:15]
	v_add_f32_e32 v240, v238, v239
	v_mov_b32_e32 v241, v240
	v_lshlrev_b32_e32 v242, 2, v32
	s_nop 0
	v_permlane32_swap_b32_e32 v241, v240
	v_add_f32_e32 v241, v241, v240
	s_mov_b64 exec, s[4:5]
	global_store_dword v242, v241, s[6:7] offset:256
	s_mov_b64 exec, -1
	s_waitcnt lgkmcnt(0)
; #define LAS __attribute__((address_space(3)))
; DI void indexer_tile(const LAS unsigned char* buf, const f16x8 (&af)[2][8], const f32x4 (&wv)[2][4], float* sc0, float* sc1, int kt, int r32, int h2) {
;     ...
;     for (int sub = 0; sub < 2; ++sub) {
;         f32x16 c0, c1;
; #pragma unroll
;         for (int i = 0; i < 16; ++i) { c0[i] = 0.f; c1[i] = 0.f; }
; #pragma unroll
;         for (int ks = 0; ks < 8; ++ks) { c0 = __builtin_amdgcn_mfma_f32_32x32x16_f16(af[0][ks], bfr[sub][ks], c0, 0, 0, 0); c1 = __builtin_amdgcn_mfma_f32_32x32x16_f16(af[1][ks], bfr[sub][ks], c1, 0, 0, 0); }
;         f32x2_t a0 = {0.f, 0.f}, a1 = {0.f, 0.f};
; #pragma unroll
;         for (int q = 0; q < 4; ++q)
; #pragma unroll
;             for (int e = 0; e < 4; e += 2) {
;                 const f32x2_t r0 = {relu1(c0[4 * q + e]), relu1(c0[4 * q + e + 1])};
;                 const f32x2_t r1 = {relu1(c1[4 * q + e]), relu1(c1[4 * q + e + 1])};
;                 const f32x2_t w0 = {wv[0][q][e], wv[0][q][e + 1]}, w1 = {wv[1][q][e], wv[1][q][e + 1]};
;                 a0 = __builtin_elementwise_fma(r0, w0, a0); a1 = __builtin_elementwise_fma(r1, w1, a1); }
;         float s0 = a0.x + a0.y, s1 = a1.x + a1.y;
;         s0 += __shfl_xor(s0, 32); s1 += __shfl_xor(s1, 32);
;         if (h2 == 0) { sc0[kt * 64 + 32 * sub + r32] = s0; sc1[kt * 64 + 32 * sub + r32] = s1; }
; DI void indexer_phase(const unsigned short* QI, const unsigned short* KI16, const float* WI, float* SC, LAS unsigned char* lds, int tid, int bid, int G) {
;     ...
;                 if (kt + 2 < nt) { *(LAS u32x4*)(buf0 + key0 * KT_ROWB + ch * 16) = a0; *(LAS u32x4*)(buf0 + (key0 + 32) * KT_ROWB + ch * 16) = a1; }
	v_mfma_f32_32x32x16_f16 v[16:31], v[34:37], v[174:177], 0
	v_mfma_f32_32x32x16_f16 v[16:31], v[38:41], v[170:173], v[16:31]
	v_mfma_f32_32x32x16_f16 v[16:31], v[42:45], v[166:169], v[16:31]
	s_nop 8
	v_max_i32_e32 v0, 0, v0
	v_max_i32_e32 v1, 0, v1
	v_fma_f32 v243, v0, v114, 0
	v_fma_f32 v244, v1, v115, 0
	v_max_i32_e32 v2, 0, v2
	v_max_i32_e32 v3, 0, v3
	v_fma_f32 v243, v2, v116, v243
	v_mfma_f32_32x32x16_f16 v[16:31], v[46:49], v[162:165], v[16:31]
	v_fma_f32 v244, v3, v117, v244
	v_max_i32_e32 v4, 0, v4
	v_max_i32_e32 v5, 0, v5
	v_fma_f32 v243, v4, v118, v243
	v_fma_f32 v244, v5, v119, v244
	v_max_i32_e32 v6, 0, v6
	v_max_i32_e32 v7, 0, v7
	v_mfma_f32_32x32x16_f16 v[16:31], v[50:53], v[158:161], v[16:31]
	v_fma_f32 v243, v6, v120, v243
	v_fma_f32 v244, v7, v121, v244
	v_max_i32_e32 v8, 0, v8
	v_max_i32_e32 v9, 0, v9
	v_fma_f32 v243, v8, v122, v243
	v_fma_f32 v244, v9, v123, v244
	v_mfma_f32_32x32x16_f16 v[16:31], v[54:57], v[154:157], v[16:31]
	v_max_i32_e32 v10, 0, v10
	v_max_i32_e32 v11, 0, v11
	v_fma_f32 v243, v10, v124, v243
	v_fma_f32 v244, v11, v125, v244
	v_max_i32_e32 v12, 0, v12
	v_max_i32_e32 v13, 0, v13
	v_mfma_f32_32x32x16_f16 v[16:31], v[58:61], v[150:153], v[16:31]
	v_fma_f32 v243, v12, v126, v243
	v_fma_f32 v244, v13, v127, v244
	v_max_i32_e32 v14, 0, v14
	v_max_i32_e32 v15, 0, v15
	v_fma_f32 v243, v14, v128, v243
	v_fma_f32 v244, v15, v129, v244
	v_mfma_f32_32x32x16_f16 v[16:31], v[62:65], v[146:149], v[16:31]
	v_add_f32_e32 v245, v243, v244
	v_mov_b32_e32 v246, v245
	v_lshlrev_b32_e32 v247, 2, v32
	s_nop 0
	v_permlane32_swap_b32_e32 v246, v245
	v_add_f32_e32 v246, v246, v245
	s_mov_b64 exec, s[4:5]
	global_store_dword v247, v246, s[8:9] offset:256
	s_mov_b64 exec, -1
	v_mfma_f32_32x32x16_f16 v[0:15], v[82:85], v[174:177], 0
	v_mfma_f32_32x32x16_f16 v[0:15], v[86:89], v[170:173], v[0:15]
	v_mfma_f32_32x32x16_f16 v[0:15], v[90:93], v[166:169], v[0:15]
	s_nop 8
	v_max_i32_e32 v16, 0, v16
	v_max_i32_e32 v17, 0, v17
	v_fma_f32 v238, v16, v66, 0
	v_fma_f32 v239, v17, v67, 0
	v_max_i32_e32 v18, 0, v18
	v_max_i32_e32 v19, 0, v19
	v_fma_f32 v238, v18, v68, v238
	v_mfma_f32_32x32x16_f16 v[0:15], v[94:97], v[162:165], v[0:15]
	v_fma_f32 v239, v19, v69, v239
	v_max_i32_e32 v20, 0, v20
	v_max_i32_e32 v21, 0, v21
	v_fma_f32 v238, v20, v70, v238
	v_fma_f32 v239, v21, v71, v239
	v_max_i32_e32 v22, 0, v22
	v_max_i32_e32 v23, 0, v23
	v_mfma_f32_32x32x16_f16 v[0:15], v[98:101], v[158:161], v[0:15]
	v_fma_f32 v238, v22, v72, v238
	v_fma_f32 v239, v23, v73, v239
	v_max_i32_e32 v24, 0, v24
	v_max_i32_e32 v25, 0, v25
	v_fma_f32 v238, v24, v74, v238
	v_fma_f32 v239, v25, v75, v239
	v_mfma_f32_32x32x16_f16 v[0:15], v[102:105], v[154:157], v[0:15]
	v_max_i32_e32 v26, 0, v26
	v_max_i32_e32 v27, 0, v27
	v_fma_f32 v238, v26, v76, v238
	v_fma_f32 v239, v27, v77, v239
	v_max_i32_e32 v28, 0, v28
	v_max_i32_e32 v29, 0, v29
	v_mfma_f32_32x32x16_f16 v[0:15], v[106:109], v[150:153], v[0:15]
	v_fma_f32 v238, v28, v78, v238
	v_fma_f32 v239, v29, v79, v239
	v_max_i32_e32 v30, 0, v30
	v_max_i32_e32 v31, 0, v31
	v_fma_f32 v238, v30, v80, v238
	v_fma_f32 v239, v31, v81, v239
	v_mfma_f32_32x32x16_f16 v[0:15], v[110:113], v[146:149], v[0:15]
	v_add_f32_e32 v240, v238, v239
	v_mov_b32_e32 v241, v240
	v_lshlrev_b32_e32 v242, 2, v32
	s_nop 0
	v_permlane32_swap_b32_e32 v241, v240
	v_add_f32_e32 v241, v241, v240
	s_mov_b64 exec, s[4:5]
	global_store_dword v242, v241, s[6:7] offset:384
	s_mov_b64 exec, -1
	s_nop 11
	v_max_i32_e32 v0, 0, v0
	v_max_i32_e32 v1, 0, v1
	v_fma_f32 v243, v0, v114, 0
	v_fma_f32 v244, v1, v115, 0
	v_max_i32_e32 v2, 0, v2
	v_max_i32_e32 v3, 0, v3
	v_fma_f32 v243, v2, v116, v243
	v_fma_f32 v244, v3, v117, v244
	v_max_i32_e32 v4, 0, v4
	v_max_i32_e32 v5, 0, v5
	v_fma_f32 v243, v4, v118, v243
	v_fma_f32 v244, v5, v119, v244
	v_max_i32_e32 v6, 0, v6
	v_max_i32_e32 v7, 0, v7
	v_fma_f32 v243, v6, v120, v243
	v_fma_f32 v244, v7, v121, v244
	v_max_i32_e32 v8, 0, v8
	v_max_i32_e32 v9, 0, v9
	v_fma_f32 v243, v8, v122, v243
	v_fma_f32 v244, v9, v123, v244
	v_max_i32_e32 v10, 0, v10
	v_max_i32_e32 v11, 0, v11
	v_fma_f32 v243, v10, v124, v243
	v_fma_f32 v244, v11, v125, v244
	v_max_i32_e32 v12, 0, v12
	v_max_i32_e32 v13, 0, v13
	v_fma_f32 v243, v12, v126, v243
	v_fma_f32 v244, v13, v127, v244
	v_max_i32_e32 v14, 0, v14
	v_max_i32_e32 v15, 0, v15
	v_fma_f32 v243, v14, v128, v243
	v_fma_f32 v244, v15, v129, v244
	v_add_f32_e32 v245, v243, v244
	v_mov_b32_e32 v246, v245
	v_lshlrev_b32_e32 v247, 2, v32
	s_nop 0
	v_permlane32_swap_b32_e32 v246, v245
	v_add_f32_e32 v246, v246, v245
	s_mov_b64 exec, s[4:5]
	global_store_dword v247, v246, s[8:9] offset:384
	s_mov_b64 exec, -1
	s_andn2_b64 vcc, exec, s[10:11]
	s_cbranch_vccnz .LBB0_1888
	s_waitcnt vmcnt(8)
	ds_write_b128 v209, v[130:133]
	ds_write_b128 v209, v[138:141] offset:8704
	s_branch .LBB0_1888

; #define LAS __attribute__((address_space(3)))
; DI __amdgpu_buffer_rsrc_t kv_rsrc(const bf16_t* base) { return __builtin_amdgcn_make_buffer_rsrc((void*)base, 0, SEQ * 256, 0x00020000); }
; DI void dsa_attn_phase(const bf16_t* Q1, const bf16_t* K1, const bf16_t* V1, const unsigned short* IDX, unsigned char* AO, LAS unsigned char* lds, int tid, int bid, int G) {
;     ...
;     u32x4 vst[8], kst[16]; bf16x8 qf[4];
;     {
;         DSA_ITEM(it, kvh, t);
; #pragma unroll
;         for (int i = 0; i < 2; ++i) ((LAS u32_alias_t*)il0)[lane + 64 * i] = __builtin_amdgcn_raw_buffer_load_b32(ir, lane * 4 + 256 * i, t * 512, 0);
;         const size_t slice = (size_t)((t >> 13) * 8 + kvh) * SEQ * 128;
;         const __amdgpu_buffer_rsrc_t kr = kv_rsrc(K1 + slice), vr = kv_rsrc(V1 + slice);
; #pragma unroll
;         for (int ks = 0; ks < 4; ++ks) qf[ks] = (n < 4) ? __builtin_bit_cast(bf16x8, __builtin_amdgcn_raw_buffer_load_b128(qr, qlo + 64 * ks, t * 8192 + kvh * 1024, 0)) : (bf16x8){0, 0, 0, 0, 0, 0, 0, 0};
; #pragma unroll
;         for (int i = 0; i < 16; ++i) kst[i] = __builtin_amdgcn_raw_buffer_load_b128(kr, (int)il0[4 * i + g4] * 256 + vvo, 0, 0);
; #pragma unroll
;         for (int i = 0; i < 8; ++i) vst[i] = __builtin_amdgcn_raw_buffer_load_b128(vr, (int)il0[4 * i + g4] * 256 + vvo, 0, 0);
;     }
;     int par = 0;
.LBB0_3323:
	s_or_b64 exec, exec, s[6:7]
	s_add_u32 s50, s82, 0x3ab00000
	s_addc_u32 s51, s83, 0
	s_add_u32 s52, s82, 0x3cb00000
	s_addc_u32 s53, s83, 0
	s_ashr_i32 s6, s12, 10
	s_and_b32 s6, s6, -8
	s_or_b32 s6, s6, s33
	s_ashr_i32 s7, s6, 31
	s_lshl_b64 s[6:7], s[6:7], 21
	s_add_u32 s24, s50, s6
	s_addc_u32 s11, s51, s7
	s_add_u32 s12, s52, s6
	s_addc_u32 s13, s53, s7
	s_add_u32 s20, s82, 0x5ab00000
	s_addc_u32 s18, s83, 0
	s_lshl_b32 s14, s88, 3
	s_and_b64 s[6:7], s[2:3], exec
	v_lshrrev_b32_e32 v204, 4, v200
	v_lshl_add_u32 v205, v204, 8, s56
	s_movk_i32 s6, 0xff02
	v_mad_i32_i24 v9, v204, s6, v205
	ds_read_u16 v10, v9 offset:16384
	ds_read_u16 v11, v9 offset:16392
	ds_read_u16 v28, v9 offset:16400
	ds_read_u16 v29, v9 offset:16408
	ds_read_u16 v30, v9 offset:16416
	ds_read_u16 v31, v9 offset:16424
	ds_read_u16 v20, v9 offset:16432
	ds_read_u16 v21, v9 offset:16440
	v_lshlrev_b32_e32 v206, 4, v117
	s_cselect_b32 s54, s88, s14
	s_mov_b32 s15, 0x20000
	s_and_b32 s13, s13, 0xffff
	s_mov_b32 s14, 0x200000
	s_waitcnt lgkmcnt(0)
	v_lshl_or_b32 v40, v21, 8, v206
	v_lshl_or_b32 v42, v31, 8, v206
	v_lshl_or_b32 v44, v29, 8, v206
	v_lshl_or_b32 v11, v11, 8, v206
	v_lshl_or_b32 v41, v20, 8, v206
	buffer_load_dwordx4 v[24:27], v40, s[12:15], 0 offen
	buffer_load_dwordx4 v[20:23], v41, s[12:15], 0 offen
	v_lshl_or_b32 v43, v30, 8, v206
	buffer_load_dwordx4 v[112:115], v42, s[12:15], 0 offen
	buffer_load_dwordx4 v[108:111], v43, s[12:15], 0 offen
	v_lshl_or_b32 v45, v28, 8, v206
	buffer_load_dwordx4 v[104:107], v44, s[12:15], 0 offen
	buffer_load_dwordx4 v[100:103], v45, s[12:15], 0 offen
	v_lshl_or_b32 v10, v10, 8, v206
	buffer_load_dwordx4 v[96:99], v11, s[12:15], 0 offen
	buffer_load_dwordx4 v[92:95], v10, s[12:15], 0 offen
	ds_read_u16 v28, v9 offset:16504
	ds_read_u16 v29, v9 offset:16496
	ds_read_u16 v36, v9 offset:16488
	ds_read_u16 v37, v9 offset:16480
	s_and_b32 s25, s11, 0xffff
	s_mov_b32 s26, s14
	s_mov_b32 s27, s15
	s_waitcnt lgkmcnt(3)
	v_lshl_or_b32 v28, v28, 8, v206
	s_waitcnt lgkmcnt(2)
	v_lshl_or_b32 v29, v29, 8, v206
	buffer_load_dwordx4 v[32:35], v28, s[24:27], 0 offen
	s_nop 0
	buffer_load_dwordx4 v[28:31], v29, s[24:27], 0 offen
	ds_read_u16 v46, v9 offset:16472
	ds_read_u16 v48, v9 offset:16464
	s_waitcnt lgkmcnt(3)
	v_lshl_or_b32 v36, v36, 8, v206
	s_waitcnt lgkmcnt(2)
	v_lshl_or_b32 v47, v37, 8, v206
	buffer_load_dwordx4 v[36:39], v36, s[24:27], 0 offen
	s_nop 0
	buffer_load_dwordx4 v[72:75], v47, s[24:27], 0 offen
	ds_read_u16 v47, v9 offset:16456
	ds_read_u16 v9, v9 offset:16448
	s_waitcnt lgkmcnt(3)
	v_lshl_or_b32 v46, v46, 8, v206
	s_waitcnt lgkmcnt(2)
	v_lshl_or_b32 v48, v48, 8, v206
	buffer_load_dwordx4 v[88:91], v46, s[24:27], 0 offen
	buffer_load_dwordx4 v[84:87], v48, s[24:27], 0 offen
	s_waitcnt lgkmcnt(1)
	v_lshl_or_b32 v46, v47, 8, v206
	s_waitcnt lgkmcnt(0)
	v_lshl_or_b32 v9, v9, 8, v206
	buffer_load_dwordx4 v[80:83], v46, s[24:27], 0 offen
	buffer_load_dwordx4 v[76:79], v9, s[24:27], 0 offen
	buffer_load_dwordx4 v[68:71], v40, s[24:27], 0 offen
	buffer_load_dwordx4 v[64:67], v41, s[24:27], 0 offen
	buffer_load_dwordx4 v[60:63], v42, s[24:27], 0 offen
	buffer_load_dwordx4 v[56:59], v43, s[24:27], 0 offen
	buffer_load_dwordx4 v[52:55], v44, s[24:27], 0 offen
	buffer_load_dwordx4 v[48:51], v45, s[24:27], 0 offen
	s_nop 0
	buffer_load_dwordx4 v[44:47], v11, s[24:27], 0 offen
	buffer_load_dwordx4 v[40:43], v10, s[24:27], 0 offen
	v_lshrrev_b32_e32 v9, 2, v117
	v_lshlrev_b32_e32 v208, 2, v204
	v_or_b32_e32 v10, v208, v9
	v_lshlrev_b32_e32 v11, 3, v116
	v_and_b32_e32 v116, 8, v11
	v_lshl_add_u32 v10, v10, 8, s56
	v_and_b32_e32 v11, 16, v11
	v_add3_u32 v210, v10, v116, v11
	v_xor_b32_e32 v10, v204, v117
	v_lshlrev_b32_e32 v211, 4, v10
	v_lshlrev_b32_e32 v212, 5, v9
	v_bitop3_b32 v9, v204, v117, 4 bitop3:0x36
	v_bitop3_b32 v10, v204, v117, 8 bitop3:0x36
	v_bitop3_b32 v11, v204, v117, 12 bitop3:0x36
	v_lshlrev_b32_e32 v116, 5, v204
	v_lshlrev_b32_e32 v213, 4, v9
	v_xor_b32_e32 v9, 32, v212
	v_lshlrev_b32_e32 v214, 4, v10
	v_xor_b32_e32 v10, 64, v212
	v_lshlrev_b32_e32 v215, 4, v11
	v_xor_b32_e32 v11, 0x60, v212
	v_xor_b32_e32 v116, v116, v206
	v_lshl_or_b32 v216, v117, 7, v208
	v_mbcnt_lo_u32_b32 v117, -1, 0
	v_or_b32_e32 v207, 0x100, v201
	s_and_b32 s21, s18, 0xffff
	s_brev_b32 s22, 32
	s_mov_b32 s23, s15
	s_add_i32 s55, s56, 0x4000
	v_add_u32_e32 v209, s56, v118
	s_addk_i32 s56, 0x4200
	v_or_b32_e32 v217, 64, v202
	v_or_b32_e32 v218, 0x80, v202
	s_lshl_b32 s57, s33, 9
	v_or_b32_e32 v219, 16, v216
	v_or_b32_e32 v220, 32, v216
	v_or_b32_e32 v221, 48, v216
	v_or_b32_e32 v222, 64, v216
	v_or_b32_e32 v223, 0x50, v216
	v_or_b32_e32 v224, 0x60, v216
	v_or_b32_e32 v225, 0x70, v216
	v_lshlrev_b32_e32 v226, 1, v204
	v_mbcnt_hi_u32_b32 v227, -1, v117
	s_mov_b32 s59, 0x3e0293ee
	v_add_u32_e32 v228, v205, v116
	s_mov_b32 s60, 0x41800000
	v_mov_b32_e32 v229, 0xff800000
	v_add_u32_e32 v230, v210, v9
	v_add_u32_e32 v231, v210, v10
	v_add_u32_e32 v232, v210, v11
	s_waitcnt vmcnt(0)
	s_branch .LBB0_3325

; #define LAS __attribute__((address_space(3)))
; DI __amdgpu_buffer_rsrc_t kv_rsrc(const bf16_t* base) { return __builtin_amdgcn_make_buffer_rsrc((void*)base, 0, SEQ * 256, 0x00020000); }
; DI void dsa_attn_phase(const bf16_t* Q1, const bf16_t* K1, const bf16_t* V1, const unsigned short* IDX, unsigned char* AO, LAS unsigned char* lds, int tid, int bid, int G) {
;     ...
;         for (int c = 0; c < 4; ++c) {
; #pragma unroll
;             for (int i = 0; i < 16; ++i) *(LAS u32x4*)(kwb[i & 3] + i * 1024) = kst[i];
;             if (c < 3) {
; #pragma unroll
;                 for (int i = 0; i < 16; ++i) kst[i] = __builtin_amdgcn_raw_buffer_load_b128(kr, (int)ilc[(c + 1) * 64 + 4 * i + g4] * 256 + vvo, 0, 0);
;             } else if (has_next) {
; #pragma unroll
;                 for (int i = 0; i < 2; ++i) ((LAS u32_alias_t*)iln)[lane + 64 * i] = inext[i];
;                 const __amdgpu_buffer_rsrc_t kr2 = kv_rsrc(K1 + slice2);
; #pragma unroll
;                 for (int i = 0; i < 16; ++i) kst[i] = __builtin_amdgcn_raw_buffer_load_b128(kr2, (int)iln[4 * i + g4] * 256 + vvo, 0, 0);
;             }
.LBB0_3328:
	s_cmpk_eq_i32 s62, 0xc0
	s_cselect_b64 s[46:47], -1, 0
	s_cmpk_lg_i32 s62, 0xc0
	s_cselect_b64 s[42:43], -1, 0
	v_add_u32_e32 v9, v205, v211
	s_waitcnt lgkmcnt(0)
	v_add_u32_e32 v10, v205, v213
	v_add_u32_e32 v11, v205, v214
	v_add_u32_e32 v148, v205, v215
	s_and_b64 vcc, exec, s[42:43]
	v_add_u32_e32 v240, s63, v226
	s_waitcnt vmcnt(8)
	ds_write_b128 v9, v[40:43]
	ds_write_b128 v10, v[44:47] offset:1024
	ds_write_b128 v11, v[48:51] offset:2048
	ds_write_b128 v148, v[52:55] offset:3072
	ds_write_b128 v9, v[56:59] offset:4096
	ds_write_b128 v10, v[60:63] offset:5120
	ds_write_b128 v11, v[64:67] offset:6144
	ds_write_b128 v148, v[68:71] offset:7168
	ds_write_b128 v9, v[76:79] offset:8192
	ds_write_b128 v10, v[80:83] offset:9216
	ds_write_b128 v11, v[84:87] offset:10240
	ds_write_b128 v148, v[88:91] offset:11264
	ds_write_b128 v9, v[72:75] offset:12288
	ds_write_b128 v10, v[36:39] offset:13312
	ds_write_b128 v11, v[28:31] offset:14336
	ds_write_b128 v148, v[32:35] offset:15360
	s_cbranch_vccz .LBB0_3331
	ds_read_u16 v9, v240 offset:128
	ds_read_u16 v10, v240 offset:136
	ds_read_u16 v11, v240 offset:144
	ds_read_u16 v48, v240 offset:152
	ds_read_u16 v56, v240 offset:160
	ds_read_u16 v57, v240 offset:168
	ds_read_u16 v64, v240 offset:176
	ds_read_u16 v65, v240 offset:184
	s_waitcnt lgkmcnt(7)
	v_lshl_or_b32 v9, v9, 8, v206
	s_mov_b32 s30, s26
	s_mov_b32 s31, s27
	s_waitcnt lgkmcnt(6)
	v_lshl_or_b32 v10, v10, 8, v206
	buffer_load_dwordx4 v[40:43], v9, s[28:31], 0 offen
	buffer_load_dwordx4 v[44:47], v10, s[28:31], 0 offen
	s_waitcnt lgkmcnt(5)
	v_lshl_or_b32 v9, v11, 8, v206
	s_waitcnt lgkmcnt(4)
	v_lshl_or_b32 v10, v48, 8, v206
	buffer_load_dwordx4 v[48:51], v9, s[28:31], 0 offen
	buffer_load_dwordx4 v[52:55], v10, s[28:31], 0 offen
	s_waitcnt lgkmcnt(3)
	v_lshl_or_b32 v9, v56, 8, v206
	s_waitcnt lgkmcnt(2)
	v_lshl_or_b32 v10, v57, 8, v206
	buffer_load_dwordx4 v[56:59], v9, s[28:31], 0 offen
	buffer_load_dwordx4 v[60:63], v10, s[28:31], 0 offen
	s_waitcnt lgkmcnt(1)
	v_lshl_or_b32 v9, v64, 8, v206
	s_waitcnt lgkmcnt(0)
	v_lshl_or_b32 v10, v65, 8, v206
	buffer_load_dwordx4 v[64:67], v9, s[28:31], 0 offen
	buffer_load_dwordx4 v[68:71], v10, s[28:31], 0 offen
	ds_read_u16 v9, v240 offset:192
	ds_read_u16 v10, v240 offset:200
	ds_read_u16 v11, v240 offset:208
	ds_read_u16 v72, v240 offset:216
	ds_read_u16 v73, v240 offset:224
	s_waitcnt lgkmcnt(4)
	v_lshl_or_b32 v9, v9, 8, v206
	s_waitcnt lgkmcnt(3)
	v_lshl_or_b32 v10, v10, 8, v206
	buffer_load_dwordx4 v[76:79], v9, s[28:31], 0 offen
	buffer_load_dwordx4 v[80:83], v10, s[28:31], 0 offen
	s_waitcnt lgkmcnt(2)
	v_lshl_or_b32 v9, v11, 8, v206
	s_waitcnt lgkmcnt(1)
	v_lshl_or_b32 v10, v72, 8, v206
	buffer_load_dwordx4 v[84:87], v9, s[28:31], 0 offen
	buffer_load_dwordx4 v[88:91], v10, s[28:31], 0 offen
	s_waitcnt lgkmcnt(0)
	v_lshl_or_b32 v9, v73, 8, v206
	buffer_load_dwordx4 v[72:75], v9, s[28:31], 0 offen
	s_add_i32 s38, s63, 0x80
	s_mov_b64 s[30:31], -1
	s_cbranch_execz .LBB0_3332
	s_mov_b64 s[12:13], s[28:29]
	s_and_b64 vcc, exec, s[30:31]
	s_cbranch_vccnz .LBB0_3335
	s_branch .LBB0_3336
.Lp13_nonext:
	s_waitcnt vmcnt(0)
	s_branch .LBB0_3334

; __device__ __forceinline__ unsigned cvt_pk_bf16(float lo, float hi) { unsigned r; asm volatile("v_cvt_pk_bf16_f32 %0, %1, %2" : "=v"(r) : "v"(lo), "v"(hi)); return r; }
; #define LAS __attribute__((address_space(3)))
; DI void dsa_attn_phase(const bf16_t* Q1, const bf16_t* K1, const bf16_t* V1, const unsigned short* IDX, unsigned char* AO, LAS unsigned char* lds, int tid, int bid, int G) {
;     ...
;             f32x4 sa[4];
; #pragma unroll
;             for (int tt = 0; tt < 4; ++tt) { f32x4 a = {0.f, 0.f, 0.f, 0.f};
; #pragma unroll
;                 for (int ks = 0; ks < 4; ++ks) { const bf16x8 kf = *(const LAS bf16x8*)(krb[ks] + tt * 4096);
;                     a = __builtin_amdgcn_mfma_f32_16x16x32_bf16(kf, qf[ks], a, 0, 0, 0); }
;                 sa[tt] = a; asm volatile("" ::: "memory"); }
;             if (nvalid < 256) {
; #pragma unroll
;                 for (int tt = 0; tt < 4; ++tt)
; #pragma unroll
;                     for (int j = 0; j < 4; ++j) { const int kk = 64 * c + 16 * tt + 4 * g4 + j; sa[tt][j] = (kk < nvalid) ? sa[tt][j] : -__builtin_inff(); }
;             }
;             float cm = fmaxf(fmaxf(fmaxf(sa[0][0], sa[0][1]), fmaxf(sa[0][2], sa[0][3])), fmaxf(fmaxf(sa[1][0], sa[1][1]), fmaxf(sa[1][2], sa[1][3])));
;             cm = fmaxf(cm, fmaxf(fmaxf(fmaxf(sa[2][0], sa[2][1]), fmaxf(sa[2][2], sa[2][3])), fmaxf(fmaxf(sa[3][0], sa[3][1]), fmaxf(sa[3][2], sa[3][3]))));
;             cm = fmaxf(cm, __shfl_xor(cm, 16)); cm = fmaxf(cm, __shfl_xor(cm, 32));
;             const float mnew = fmaxf(mrun, cm); const float alpha = __builtin_amdgcn_exp2f((mrun - mnew) * SM_C); const float msc = mnew * SM_C; mrun = mnew;
;             lsum *= alpha;
; #pragma unroll
;             for (int dt = 0; dt < 8; ++dt) o[dt] = o[dt] * alpha;
;             unsigned pk[4][2];
; #pragma unroll
;             for (int tt = 0; tt < 4; ++tt) { float pp[4];
; #pragma unroll
;                 for (int j = 0; j < 4; ++j) { pp[j] = __builtin_amdgcn_exp2f(sa[tt][j] * SM_C - msc); lsum += pp[j]; }
;                 pk[tt][0] = pg8::cvt_pk_bf16(pp[0], pp[1]); pk[tt][1] = pg8::cvt_pk_bf16(pp[2], pp[3]); }
;             if (c == 3 && has_next) {
; #pragma unroll
;                 for (int ks = 0; ks < 4; ++ks) qf[ks] = (n < 4) ? __builtin_bit_cast(bf16x8, __builtin_amdgcn_raw_buffer_load_b128(qr, qlo + 64 * ks, t2 * 8192 + kvh2 * 1024, 0)) : (bf16x8){0, 0, 0, 0, 0, 0, 0, 0};
.LBB0_3336:
	v_add_u32_e32 v9, v209, v211
	ds_read_b128 v[148:151], v9
	v_add_u32_e32 v10, v209, v213
	v_add_u32_e32 v11, v209, v214
	v_add_u32_e32 v172, v209, v215
	ds_read_b128 v[152:155], v10
	ds_read_b128 v[156:159], v11
	ds_read_b128 v[160:163], v172
	ds_read_b128 v[164:167], v9 offset:4096
	ds_read_b128 v[168:171], v10 offset:4096
	s_waitcnt lgkmcnt(1)
	v_mfma_f32_16x16x32_bf16 v[164:167], v[164:167], v[0:3], 0
	s_andn2_b64 vcc, exec, s[44:45]
	v_mfma_f32_16x16x32_bf16 v[148:151], v[148:151], v[0:3], 0
	v_mfma_f32_16x16x32_bf16 v[148:151], v[152:155], v[4:7], v[148:151]
	v_mfma_f32_16x16x32_bf16 v[148:151], v[156:159], v[12:15], v[148:151]
	v_mfma_f32_16x16x32_bf16 v[152:155], v[160:163], v[16:19], v[148:151]
	ds_read_b128 v[156:159], v11 offset:4096
	ds_read_b128 v[160:163], v172 offset:4096
	s_waitcnt lgkmcnt(2)
	v_mfma_f32_16x16x32_bf16 v[148:151], v[168:171], v[4:7], v[164:167]
	s_waitcnt lgkmcnt(1)
	v_mfma_f32_16x16x32_bf16 v[148:151], v[156:159], v[12:15], v[148:151]
	ds_read_b128 v[156:159], v9 offset:8192
	ds_read_b128 v[164:167], v11 offset:8192
	s_waitcnt lgkmcnt(2)
	v_mfma_f32_16x16x32_bf16 v[148:151], v[160:163], v[16:19], v[148:151]
	ds_read_b128 v[160:163], v10 offset:8192
	s_waitcnt lgkmcnt(2)
	v_mfma_f32_16x16x32_bf16 v[156:159], v[156:159], v[0:3], 0
	s_waitcnt lgkmcnt(0)
	v_mfma_f32_16x16x32_bf16 v[156:159], v[160:163], v[4:7], v[156:159]
	ds_read_b128 v[160:163], v172 offset:8192
	ds_read_b128 v[168:171], v11 offset:12288
	v_mfma_f32_16x16x32_bf16 v[156:159], v[164:167], v[12:15], v[156:159]
	ds_read_b128 v[164:167], v9 offset:12288
	s_waitcnt lgkmcnt(2)
	v_mfma_f32_16x16x32_bf16 v[156:159], v[160:163], v[16:19], v[156:159]
	ds_read_b128 v[160:163], v10 offset:12288
	s_waitcnt lgkmcnt(1)
	v_mfma_f32_16x16x32_bf16 v[164:167], v[164:167], v[0:3], 0
	s_waitcnt lgkmcnt(0)
	v_mfma_f32_16x16x32_bf16 v[160:163], v[160:163], v[4:7], v[164:167]
	s_nop 5
	ds_read_b128 v[164:167], v172 offset:12288
	v_mfma_f32_16x16x32_bf16 v[160:163], v[168:171], v[12:15], v[160:163]
	s_waitcnt lgkmcnt(0)
	v_mfma_f32_16x16x32_bf16 v[160:163], v[164:167], v[16:19], v[160:163]
	s_cbranch_vccnz .LBB0_3338
	v_add_u32_e32 v9, s62, v208
	v_cmp_ge_u32_e32 vcc, s65, v9
	v_add_u32_e32 v10, 2, v9
	s_nop 0
	v_cndmask_b32_e32 v152, v229, v152, vcc
	v_cmp_gt_u32_e32 vcc, s65, v9
	s_nop 1
	v_cndmask_b32_e32 v153, v229, v153, vcc
	v_cmp_ge_u32_e32 vcc, s65, v10
	v_add_u32_e32 v10, 3, v9
	s_nop 0
	v_cndmask_b32_e32 v154, v229, v154, vcc
	v_cmp_ge_u32_e32 vcc, s65, v10
	v_add_u32_e32 v10, 16, v9
	s_nop 0
	v_cndmask_b32_e32 v155, v229, v155, vcc
	v_cmp_ge_u32_e32 vcc, s65, v10
	v_add_u32_e32 v10, 17, v9
	s_nop 0
	v_cndmask_b32_e32 v148, v229, v148, vcc
	v_cmp_ge_u32_e32 vcc, s65, v10
	v_add_u32_e32 v10, 18, v9
	s_nop 0
	v_cndmask_b32_e32 v149, v229, v149, vcc
	v_cmp_ge_u32_e32 vcc, s65, v10
	v_add_u32_e32 v10, 19, v9
	s_nop 0
	v_cndmask_b32_e32 v150, v229, v150, vcc
	v_cmp_ge_u32_e32 vcc, s65, v10
	v_add_u32_e32 v10, 32, v9
	s_nop 0
	v_cndmask_b32_e32 v151, v229, v151, vcc
	v_cmp_ge_u32_e32 vcc, s65, v10
	v_add_u32_e32 v10, 33, v9
	s_nop 0
	v_cndmask_b32_e32 v156, v229, v156, vcc
	v_cmp_ge_u32_e32 vcc, s65, v10
	v_add_u32_e32 v10, 34, v9
	s_nop 0
	v_cndmask_b32_e32 v157, v229, v157, vcc
	v_cmp_ge_u32_e32 vcc, s65, v10
	v_add_u32_e32 v10, 35, v9
	s_nop 0
	v_cndmask_b32_e32 v158, v229, v158, vcc
	v_cmp_ge_u32_e32 vcc, s65, v10
	v_add_u32_e32 v10, 48, v9
	s_nop 0
	v_cndmask_b32_e32 v159, v229, v159, vcc
	v_cmp_ge_u32_e32 vcc, s65, v10
	v_add_u32_e32 v10, 49, v9
	s_nop 0
	v_cndmask_b32_e32 v160, v229, v160, vcc
	v_cmp_ge_u32_e32 vcc, s65, v10
	v_add_u32_e32 v10, 50, v9
	v_add_u32_e32 v9, 51, v9
	v_cndmask_b32_e32 v161, v229, v161, vcc
	v_cmp_ge_u32_e32 vcc, s65, v10
	s_nop 1
	v_cndmask_b32_e32 v162, v229, v162, vcc
	v_cmp_ge_u32_e32 vcc, s65, v9
	s_nop 1
	v_cndmask_b32_e32 v163, v229, v163, vcc
.LBB0_3338:
	v_max_f32_e32 v9, v155, v155
	v_max_f32_e32 v10, v154, v154
	v_max_f32_e32 v9, v10, v9
	v_max_f32_e32 v10, v151, v151
	v_max_f32_e32 v11, v150, v150
	v_max_f32_e32 v10, v11, v10
	v_max_f32_e32 v11, v157, v157
	v_max_f32_e32 v164, v156, v156
	v_max_f32_e32 v11, v164, v11
	v_max_f32_e32 v164, v159, v159
	v_max_f32_e32 v165, v158, v158
	v_max_f32_e32 v164, v165, v164
	v_max_f32_e32 v165, v163, v163
	v_max_f32_e32 v166, v162, v162
	v_max_f32_e32 v165, v166, v165
	v_max3_f32 v165, v160, v161, v165
	v_max3_f32 v9, v152, v153, v9
	v_max3_f32 v10, v148, v149, v10
	v_max3_f32 v11, v11, v164, v165
	v_max3_f32 v9, v9, v10, v11
	v_and_b32_e32 v11, 64, v227
	v_xor_b32_e32 v10, 16, v227
	v_add_u32_e32 v11, 64, v11
	v_cmp_lt_i32_e32 vcc, v10, v11
	s_and_b64 s[12:13], s[18:19], s[46:47]
	s_nop 0
	v_cndmask_b32_e32 v10, v227, v10, vcc
	v_lshlrev_b32_e32 v193, 2, v10
	ds_bpermute_b32 v10, v193, v9
	s_waitcnt lgkmcnt(0)
	v_max_f32_e32 v10, v10, v10
	v_max_f32_e32 v9, v9, v10
	v_xor_b32_e32 v10, 32, v227
	v_cmp_lt_i32_e32 vcc, v10, v11
	s_nop 1
	v_cndmask_b32_e32 v10, v227, v10, vcc
	v_lshlrev_b32_e32 v194, 2, v10
	ds_bpermute_b32 v10, v194, v9
	s_andn2_b64 vcc, exec, s[12:13]
	s_waitcnt lgkmcnt(0)
	v_max3_f32 v192, v239, v9, v10
	v_mul_f32_e32 v9, 0x3e0293ee, v192
	v_fma_f32 v10, v152, s59, -v9
	v_exp_f32_e32 v248, v10
	v_fma_f32 v10, v153, s59, -v9
	v_exp_f32_e32 v249, v10
	v_fma_f32 v10, v154, s59, -v9
	v_exp_f32_e32 v250, v10
	v_fma_f32 v10, v155, s59, -v9
	v_exp_f32_e32 v251, v10
	v_fma_f32 v10, v148, s59, -v9
	v_exp_f32_e32 v246, v10
	v_fma_f32 v10, v149, s59, -v9
	v_exp_f32_e32 v247, v10
	v_fma_f32 v10, v150, s59, -v9
	v_exp_f32_e32 v245, v10
	v_fma_f32 v10, v151, s59, -v9
	v_exp_f32_e32 v244, v10
	v_fma_f32 v10, v156, s59, -v9
	v_exp_f32_e32 v243, v10
	v_fma_f32 v10, v157, s59, -v9
	v_exp_f32_e32 v199, v10
	v_fma_f32 v10, v158, s59, -v9
	v_exp_f32_e32 v195, v10
	v_fma_f32 v10, v159, s59, -v9
	v_exp_f32_e32 v196, v10
	v_fma_f32 v10, v160, s59, -v9
	v_exp_f32_e32 v197, v10
	v_fma_f32 v10, v161, s59, -v9
	v_exp_f32_e32 v198, v10
	v_fma_f32 v10, v162, s59, -v9
	v_fma_f32 v9, v163, s59, -v9
	v_exp_f32_e32 v241, v10
	v_exp_f32_e32 v242, v9
	v_cvt_pk_bf16_f32 v152, v248, v249
	v_cvt_pk_bf16_f32 v153, v250, v251
	v_cvt_pk_bf16_f32 v154, v246, v247
	v_cvt_pk_bf16_f32 v155, v245, v244
	v_cvt_pk_bf16_f32 v148, v243, v199
	v_cvt_pk_bf16_f32 v149, v195, v196
	v_cvt_pk_bf16_f32 v150, v197, v198
	v_cvt_pk_bf16_f32 v151, v241, v242
	s_cbranch_vccnz .LBB0_3348
	s_waitcnt vmcnt(16)
	v_mov_b32_e32 v4, v8
	v_mov_b32_e32 v5, v8
	v_mov_b32_e32 v6, v8
	v_mov_b32_e32 v7, v8
	v_mov_b64_e32 v[0:1], v[4:5]
	v_mov_b64_e32 v[2:3], v[6:7]
	s_and_saveexec_b64 s[12:13], s[4:5]
	s_cbranch_execz .LBB0_3341
	buffer_load_dwordx4 v[0:3], v202, s[84:87], s66 offen

; DI void dsa_attn_phase(const bf16_t* Q1, const bf16_t* K1, const bf16_t* V1, const unsigned short* IDX, unsigned char* AO, LAS unsigned char* lds, int tid, int bid, int G) {
;     ...
;             const float mnew = fmaxf(mrun, cm); const float alpha = __builtin_amdgcn_exp2f((mrun - mnew) * SM_C); const float msc = mnew * SM_C; mrun = mnew;
;             lsum *= alpha;
; #pragma unroll
;             for (int dt = 0; dt < 8; ++dt) o[dt] = o[dt] * alpha;
;             unsigned pk[4][2];
; #pragma unroll
;             for (int tt = 0; tt < 4; ++tt) { float pp[4];
; #pragma unroll
;                 for (int j = 0; j < 4; ++j) { pp[j] = __builtin_amdgcn_exp2f(sa[tt][j] * SM_C - msc); lsum += pp[j]; }
;                 pk[tt][0] = pg8::cvt_pk_bf16(pp[0], pp[1]); pk[tt][1] = pg8::cvt_pk_bf16(pp[2], pp[3]); }
;             if (c == 3 && has_next) {
; #pragma unroll
;                 for (int ks = 0; ks < 4; ++ks) qf[ks] = (n < 4) ? __builtin_bit_cast(bf16x8, __builtin_amdgcn_raw_buffer_load_b128(qr, qlo + 64 * ks, t2 * 8192 + kvh2 * 1024, 0)) : (bf16x8){0, 0, 0, 0, 0, 0, 0, 0};
;             }
; #pragma unroll
;             for (int hf = 0; hf < 2; ++hf) {
; #pragma unroll
;                 for (int i = 0; i < 8; ++i) *(LAS u32x4*)(vwb + i * 1024) = vst[i];
;                 if (hf == 0) {
; #pragma unroll
;                     for (int i = 0; i < 8; ++i) vst[i] = __builtin_amdgcn_raw_buffer_load_b128(vr, (int)ilc[c * 64 + 32 + 4 * i + g4] * 256 + vvo, 0, 0);
;                 } else if (c < 3) {
; #pragma unroll
;                     for (int i = 0; i < 8; ++i) vst[i] = __builtin_amdgcn_raw_buffer_load_b128(vr, (int)ilc[(c + 1) * 64 + 4 * i + g4] * 256 + vvo, 0, 0);
;                 } else if (has_next) {
;                     const __amdgpu_buffer_rsrc_t vr2 = kv_rsrc(V1 + slice2);
; #pragma unroll
;                     for (int i = 0; i < 8; ++i) vst[i] = __builtin_amdgcn_raw_buffer_load_b128(vr2, (int)iln[4 * i + g4] * 256 + vvo, 0, 0);
;                 }
;                 u32x4 pw; pw.x = pk[2 * hf][0]; pw.y = pk[2 * hf][1]; pw.z = pk[2 * hf + 1][0]; pw.w = pk[2 * hf + 1][1];
;                 const bf16x8 pf = __builtin_bit_cast(bf16x8, pw);
; #pragma unroll
;                 for (int dt = 0; dt < 8; ++dt) {
;                     const s16x4 lo = __builtin_amdgcn_ds_read_tr16_b64_v4i16((LAS s16x4*)(trb[dt & 3] + 128 * (dt >> 2)));
.LBB0_3348:
	s_waitcnt vmcnt(16)
	ds_write_b128 v228, v[92:95]
	ds_write_b128 v228, v[96:99] offset:1024
	ds_write_b128 v228, v[100:103] offset:2048
	ds_write_b128 v228, v[104:107] offset:3072
	ds_write_b128 v228, v[108:111] offset:4096
	ds_write_b128 v228, v[112:115] offset:5120
	ds_write_b128 v228, v[20:23] offset:6144
	ds_write_b128 v228, v[24:27] offset:7168
	ds_read_u16 v9, v240 offset:64
	ds_read_u16 v10, v240 offset:72
	ds_read_u16 v11, v240 offset:80
	ds_read_u16 v20, v240 offset:88
	ds_read_u16 v21, v240 offset:96
	ds_read_u16 v22, v240 offset:104
	ds_read_u16 v23, v240 offset:112
	ds_read_u16 v24, v240 offset:120
	s_waitcnt lgkmcnt(7)
	v_lshl_or_b32 v9, v9, 8, v206
	s_waitcnt lgkmcnt(6)
	v_lshl_or_b32 v10, v10, 8, v206
	buffer_load_dwordx4 v[168:171], v9, s[24:27], 0 offen
	buffer_load_dwordx4 v[172:175], v10, s[24:27], 0 offen
	s_waitcnt lgkmcnt(5)
	v_lshl_or_b32 v9, v11, 8, v206
	s_waitcnt lgkmcnt(4)
	v_lshl_or_b32 v10, v20, 8, v206
	buffer_load_dwordx4 v[176:179], v9, s[24:27], 0 offen
	buffer_load_dwordx4 v[180:183], v10, s[24:27], 0 offen
	s_waitcnt lgkmcnt(3)
	v_lshl_or_b32 v9, v21, 8, v206
	s_waitcnt lgkmcnt(2)
	v_lshl_or_b32 v10, v22, 8, v206
	buffer_load_dwordx4 v[184:187], v9, s[24:27], 0 offen
	buffer_load_dwordx4 v[188:191], v10, s[24:27], 0 offen
	s_waitcnt lgkmcnt(1)
	v_lshl_or_b32 v9, v23, 8, v206
	buffer_load_dwordx4 v[20:23], v9, s[24:27], 0 offen
	s_waitcnt lgkmcnt(0)
	v_lshl_or_b32 v9, v24, 8, v206
	buffer_load_dwordx4 v[24:27], v9, s[24:27], 0 offen
	v_sub_f32_e32 v10, v239, v192
	v_mul_f32_e32 v10, 0x3e0293ee, v10
	v_exp_f32_e32 v10, v10
	v_add_u32_e32 v9, v210, v212
	ds_read_b64_tr_b16 v[92:93], v9
	ds_read_b64_tr_b16 v[94:95], v9 offset:4096
	ds_read_b64_tr_b16 v[96:97], v230
	ds_read_b64_tr_b16 v[98:99], v230 offset:4096
	v_pk_mul_f32 v[102:103], v[146:147], v[10:11] op_sel_hi:[1,0]
	v_pk_mul_f32 v[100:101], v[144:145], v[10:11] op_sel_hi:[1,0]
	v_pk_mul_f32 v[106:107], v[142:143], v[10:11] op_sel_hi:[1,0]
	v_pk_mul_f32 v[104:105], v[140:141], v[10:11] op_sel_hi:[1,0]
	v_pk_mul_f32 v[112:113], v[132:133], v[10:11] op_sel_hi:[1,0]
	v_pk_mul_f32 v[140:141], v[130:131], v[10:11] op_sel_hi:[1,0]
	ds_read_b64_tr_b16 v[142:143], v231
	ds_read_b64_tr_b16 v[144:145], v231 offset:4096
	s_waitcnt lgkmcnt(4)
	v_mfma_f32_16x16x32_bf16 v[130:133], v[92:95], v[152:155], v[100:103]
	ds_read_b64_tr_b16 v[92:93], v232
	ds_read_b64_tr_b16 v[94:95], v232 offset:4096
	v_pk_mul_f32 v[108:109], v[136:137], v[10:11] op_sel_hi:[1,0]
	v_pk_mul_f32 v[114:115], v[134:135], v[10:11] op_sel_hi:[1,0]
	s_waitcnt lgkmcnt(4)
	v_mfma_f32_16x16x32_bf16 v[134:137], v[96:99], v[152:155], v[104:107]
	ds_read_b64_tr_b16 v[96:97], v9 offset:128
	ds_read_b64_tr_b16 v[98:99], v9 offset:4224
	ds_read_b64_tr_b16 v[102:103], v230 offset:128
	ds_read_b64_tr_b16 v[104:105], v230 offset:4224
	v_pk_mul_f32 v[110:111], v[138:139], v[10:11] op_sel_hi:[1,0]
	v_pk_mul_f32 v[138:139], v[128:129], v[10:11] op_sel_hi:[1,0]
	v_pk_mul_f32 v[100:101], v[126:127], v[10:11] op_sel_hi:[1,0]
	s_waitcnt lgkmcnt(4)
	v_mfma_f32_16x16x32_bf16 v[126:129], v[92:95], v[152:155], v[112:115]
	ds_read_b64_tr_b16 v[92:93], v231 offset:128
	ds_read_b64_tr_b16 v[94:95], v231 offset:4224
	s_andn2_b64 vcc, exec, s[42:43]
	v_mfma_f32_16x16x32_bf16 v[156:159], v[142:145], v[152:155], v[108:111]
	ds_read_b64_tr_b16 v[106:107], v232 offset:128
	s_nop 1
	ds_read_b64_tr_b16 v[108:109], v232 offset:4224
	s_waitcnt vmcnt(7)
	ds_write_b128 v228, v[168:171]
	s_waitcnt vmcnt(6)
	ds_write_b128 v228, v[172:175] offset:1024
	s_waitcnt vmcnt(5)
	ds_write_b128 v228, v[176:179] offset:2048
	s_waitcnt vmcnt(4)
	ds_write_b128 v228, v[180:183] offset:3072
	s_waitcnt vmcnt(3)
	ds_write_b128 v228, v[184:187] offset:4096
	s_waitcnt vmcnt(2)
	ds_write_b128 v228, v[188:191] offset:5120
	s_waitcnt vmcnt(1)
	ds_write_b128 v228, v[20:23] offset:6144
	s_waitcnt lgkmcnt(13)
	v_mfma_f32_16x16x32_bf16 v[160:163], v[96:99], v[152:155], v[138:141]
	v_mul_f32_e64 v98, v124, v10
	v_mul_f32_e64 v99, v125, v10
	v_pk_mul_f32 v[96:97], v[120:121], v[10:11] op_sel_hi:[1,0]
	s_waitcnt vmcnt(0)
	ds_write_b128 v228, v[24:27] offset:7168
	s_waitcnt lgkmcnt(12)
	v_mfma_f32_16x16x32_bf16 v[164:167], v[102:105], v[152:155], v[98:101]
	s_nop 2
	v_mul_f32_e64 v98, v122, v10
	v_mul_f32_e64 v99, v123, v10
	s_waitcnt lgkmcnt(10)
	s_nop 0
	v_mfma_f32_16x16x32_bf16 v[120:123], v[92:95], v[152:155], v[96:99]
	v_mul_f32_e64 v94, v118, v10
	v_mul_f32_e64 v95, v119, v10
	v_pk_mul_f32 v[92:93], v[116:117], v[10:11] op_sel_hi:[1,0]
	s_waitcnt lgkmcnt(8)
	s_nop 0
	v_mfma_f32_16x16x32_bf16 v[116:119], v[106:109], v[152:155], v[92:95]
	s_cbranch_vccnz .LBB0_3351
	ds_read_u16 v11, v240 offset:128
	s_nop 0
	ds_read_u16 v92, v240 offset:136
	ds_read_u16 v100, v240 offset:144
	ds_read_u16 v101, v240 offset:152
	ds_read_u16 v108, v240 offset:160
	ds_read_u16 v109, v240 offset:168
	s_waitcnt lgkmcnt(5)
	v_lshl_or_b32 v11, v11, 8, v206
	s_waitcnt lgkmcnt(4)
	v_lshl_or_b32 v96, v92, 8, v206
	buffer_load_dwordx4 v[92:95], v11, s[24:27], 0 offen
	s_nop 0
	buffer_load_dwordx4 v[96:99], v96, s[24:27], 0 offen
	s_waitcnt lgkmcnt(3)
	v_lshl_or_b32 v11, v100, 8, v206
	s_waitcnt lgkmcnt(2)
	v_lshl_or_b32 v104, v101, 8, v206
	buffer_load_dwordx4 v[100:103], v11, s[24:27], 0 offen
	s_nop 0
	buffer_load_dwordx4 v[104:107], v104, s[24:27], 0 offen
	s_waitcnt lgkmcnt(1)
	v_lshl_or_b32 v11, v108, 8, v206
	s_waitcnt lgkmcnt(0)
	v_lshl_or_b32 v112, v109, 8, v206
	buffer_load_dwordx4 v[108:111], v11, s[24:27], 0 offen
	s_nop 0
	buffer_load_dwordx4 v[112:115], v112, s[24:27], 0 offen
	s_add_i32 s38, s63, 0x80
	v_add_u32_e32 v11, 0xb0, v240
	s_mov_b64 s[30:31], -1
	s_cbranch_execz .LBB0_3352
	s_mov_b64 s[12:13], s[24:25]
	s_and_b64 vcc, exec, s[30:31]
	s_cbranch_vccnz .LBB0_3355
	s_branch .LBB0_3356
